# cross-attention q-tile loop: LDS fragment reads issued one MFMA earlier (two in flight, second fragment register), exact lgkmcnt waits
# speedup vs baseline: 1.0026x; 1.0026x over previous
.LBB0_1114:
	s_waitcnt vmcnt(15)
	v_mov_b64_e32 v[182:183], v[52:53]
	v_mov_b64_e32 v[180:181], v[50:51]
	v_lshl_add_u64 v[50:51], v[136:137], 0, s[0:1]
	v_add_co_u32_e32 v222, vcc, s18, v50
	s_waitcnt vmcnt(14)
	v_mov_b64_e32 v[178:179], v[56:57]
	v_addc_co_u32_e32 v223, vcc, 0, v51, vcc
	s_waitcnt vmcnt(13)
	ds_write_b128 v173, v[58:61]
	s_waitcnt vmcnt(11)
	ds_write_b128 v173, v[62:65] offset:9216
	v_lshl_add_u64 v[220:221], v[138:139], 0, s[0:1]
	v_add_co_u32_e32 v224, vcc, s19, v50
	v_mov_b64_e32 v[176:177], v[54:55]
	s_nop 0
	v_addc_co_u32_e32 v225, vcc, 0, v51, vcc
	global_load_dwordx4 v[50:53], v[220:221], off offset:-256
	global_load_dwordx4 v[54:57], v[220:221], off offset:-192
	global_load_dwordx4 v[58:61], v[222:223], off offset:512
	global_load_dwordx4 v[62:65], v[224:225], off offset:512
	s_waitcnt lgkmcnt(0)
	s_barrier
	ds_read_b128 v[184:187], v1
	ds_read_b128 v[188:191], v1 offset:64
	ds_read_b128 v[236:239], v1 offset:2304
	ds_read_b128 v[192:195], v1 offset:2368
	s_waitcnt lgkmcnt(3)
	v_mfma_f32_16x16x32_bf16 v[94:97], v[180:183], v[184:187], v[94:97]
	s_add_u32 s0, s0, 0x200
	s_addc_u32 s1, s1, 0
	ds_read_b128 v[184:187], v1 offset:4608
	ds_read_b128 v[196:199], v1 offset:4672
	s_waitcnt lgkmcnt(3)
	v_mfma_f32_16x16x32_bf16 v[90:93], v[180:183], v[236:239], v[90:93]
	s_cmpk_lg_i32 s0, 0xe00
	ds_read_b128 v[236:239], v1 offset:6912
	ds_read_b128 v[200:203], v1 offset:6976
	s_waitcnt lgkmcnt(3)
	v_mfma_f32_16x16x32_bf16 v[86:89], v[180:183], v[184:187], v[86:89]
	ds_read_b128 v[184:187], v1 offset:9216
	ds_read_b128 v[204:207], v1 offset:9280
	s_waitcnt lgkmcnt(3)
	v_mfma_f32_16x16x32_bf16 v[82:85], v[180:183], v[236:239], v[82:85]
	ds_read_b128 v[236:239], v1 offset:11520
	ds_read_b128 v[208:211], v1 offset:11584
	s_waitcnt lgkmcnt(3)
	v_mfma_f32_16x16x32_bf16 v[78:81], v[180:183], v[184:187], v[78:81]
	ds_read_b128 v[184:187], v1 offset:13824
	ds_read_b128 v[212:215], v1 offset:13888
	s_waitcnt lgkmcnt(3)
	v_mfma_f32_16x16x32_bf16 v[70:73], v[180:183], v[236:239], v[70:73]
	ds_read_b128 v[236:239], v1 offset:16128
	ds_read_b128 v[216:219], v1 offset:16192
	s_waitcnt lgkmcnt(3)
	v_mfma_f32_16x16x32_bf16 v[66:69], v[180:183], v[184:187], v[66:69]
	ds_write_b128 v173, v[46:49] offset:18432
	s_waitcnt vmcnt(14)
	ds_write_b128 v173, v[42:45] offset:27648
	global_load_dwordx4 v[46:49], v[222:223], off offset:640
	s_waitcnt lgkmcnt(3)
	v_mfma_f32_16x16x32_bf16 v[74:77], v[180:183], v[236:239], v[74:77]
	s_waitcnt vmcnt(14)
	v_mov_b64_e32 v[186:187], v[36:37]
	s_waitcnt vmcnt(13)
	v_mov_b64_e32 v[182:183], v[40:41]
	v_mov_b64_e32 v[184:185], v[34:35]
	v_mfma_f32_16x16x32_bf16 v[94:97], v[176:179], v[188:191], v[94:97]
	v_mov_b64_e32 v[180:181], v[38:39]
	global_load_dwordx4 v[42:45], v[224:225], off offset:640
	global_load_dwordx4 v[34:37], v[220:221], off offset:-128
	global_load_dwordx4 v[38:41], v[220:221], off offset:-64
	s_waitcnt lgkmcnt(0)
	v_mfma_f32_16x16x32_bf16 v[90:93], v[176:179], v[192:195], v[90:93]
	s_barrier
	v_mfma_f32_16x16x32_bf16 v[86:89], v[176:179], v[196:199], v[86:89]
	v_mfma_f32_16x16x32_bf16 v[82:85], v[176:179], v[200:203], v[82:85]
	v_mfma_f32_16x16x32_bf16 v[78:81], v[176:179], v[204:207], v[78:81]
	v_mfma_f32_16x16x32_bf16 v[70:73], v[176:179], v[208:211], v[70:73]
	v_mfma_f32_16x16x32_bf16 v[66:69], v[176:179], v[212:215], v[66:69]
	v_mfma_f32_16x16x32_bf16 v[74:77], v[176:179], v[216:219], v[74:77]
	ds_read_b128 v[176:179], v1 offset:18432
	ds_read_b128 v[188:191], v1 offset:18496
	ds_read_b128 v[236:239], v1 offset:20736
	ds_read_b128 v[192:195], v1 offset:20800
	s_waitcnt lgkmcnt(3)
	v_mfma_f32_16x16x32_bf16 v[94:97], v[184:187], v[176:179], v[94:97]
	ds_read_b128 v[176:179], v1 offset:23040
	ds_read_b128 v[196:199], v1 offset:23104
	s_waitcnt lgkmcnt(3)
	v_mfma_f32_16x16x32_bf16 v[90:93], v[184:187], v[236:239], v[90:93]
	ds_read_b128 v[236:239], v1 offset:25344
	ds_read_b128 v[200:203], v1 offset:25408
	s_waitcnt lgkmcnt(3)
	v_mfma_f32_16x16x32_bf16 v[86:89], v[184:187], v[176:179], v[86:89]
	ds_read_b128 v[176:179], v1 offset:27648
	ds_read_b128 v[204:207], v1 offset:27712
	s_waitcnt lgkmcnt(3)
	v_mfma_f32_16x16x32_bf16 v[82:85], v[184:187], v[236:239], v[82:85]
	ds_read_b128 v[236:239], v1 offset:29952
	ds_read_b128 v[208:211], v1 offset:30016
	s_waitcnt lgkmcnt(3)
	v_mfma_f32_16x16x32_bf16 v[78:81], v[184:187], v[176:179], v[78:81]
	ds_read_b128 v[176:179], v1 offset:32256
	ds_read_b128 v[212:215], v1 offset:32320
	s_waitcnt lgkmcnt(3)
	v_mfma_f32_16x16x32_bf16 v[70:73], v[184:187], v[236:239], v[70:73]
	ds_read_b128 v[236:239], v1 offset:34560
	ds_read_b128 v[216:219], v1 offset:34624
	s_waitcnt lgkmcnt(3)
	v_mfma_f32_16x16x32_bf16 v[66:69], v[184:187], v[176:179], v[66:69]
	s_waitcnt vmcnt(13)
	ds_write_b128 v173, v[26:29]
	s_waitcnt vmcnt(11)
	ds_write_b128 v173, v[30:33] offset:9216
	global_load_dwordx4 v[26:29], v[222:223], off offset:768
	s_waitcnt lgkmcnt(3)
	v_mfma_f32_16x16x32_bf16 v[74:77], v[184:187], v[236:239], v[74:77]
	v_mov_b64_e32 v[186:187], v[20:21]
	v_mov_b64_e32 v[178:179], v[24:25]
	v_mov_b64_e32 v[184:185], v[18:19]
	v_mfma_f32_16x16x32_bf16 v[94:97], v[180:183], v[188:191], v[94:97]
	v_mov_b64_e32 v[176:177], v[22:23]
	global_load_dwordx4 v[30:33], v[224:225], off offset:768
	global_load_dwordx4 v[18:21], v[220:221], off
	global_load_dwordx4 v[22:25], v[220:221], off offset:64
	s_waitcnt lgkmcnt(0)
	v_mfma_f32_16x16x32_bf16 v[90:93], v[180:183], v[192:195], v[90:93]
	s_barrier
	v_mfma_f32_16x16x32_bf16 v[86:89], v[180:183], v[196:199], v[86:89]
	v_mfma_f32_16x16x32_bf16 v[82:85], v[180:183], v[200:203], v[82:85]
	v_mfma_f32_16x16x32_bf16 v[78:81], v[180:183], v[204:207], v[78:81]
	v_mfma_f32_16x16x32_bf16 v[70:73], v[180:183], v[208:211], v[70:73]
	v_mfma_f32_16x16x32_bf16 v[66:69], v[180:183], v[212:215], v[66:69]
	v_mfma_f32_16x16x32_bf16 v[74:77], v[180:183], v[216:219], v[74:77]
	ds_read_b128 v[180:183], v1
	ds_read_b128 v[188:191], v1 offset:64
	ds_read_b128 v[236:239], v1 offset:2304
	ds_read_b128 v[192:195], v1 offset:2368
	s_waitcnt lgkmcnt(3)
	v_mfma_f32_16x16x32_bf16 v[94:97], v[184:187], v[180:183], v[94:97]
	ds_read_b128 v[180:183], v1 offset:4608
	ds_read_b128 v[196:199], v1 offset:4672
	s_waitcnt lgkmcnt(3)
	v_mfma_f32_16x16x32_bf16 v[90:93], v[184:187], v[236:239], v[90:93]
	ds_read_b128 v[236:239], v1 offset:6912
	ds_read_b128 v[200:203], v1 offset:6976
	s_waitcnt lgkmcnt(3)
	v_mfma_f32_16x16x32_bf16 v[86:89], v[184:187], v[180:183], v[86:89]
	ds_read_b128 v[180:183], v1 offset:9216
	ds_read_b128 v[204:207], v1 offset:9280
	s_waitcnt lgkmcnt(3)
	v_mfma_f32_16x16x32_bf16 v[82:85], v[184:187], v[236:239], v[82:85]
	ds_read_b128 v[236:239], v1 offset:11520
	ds_read_b128 v[208:211], v1 offset:11584
	s_waitcnt lgkmcnt(3)
	v_mfma_f32_16x16x32_bf16 v[78:81], v[184:187], v[180:183], v[78:81]
	ds_read_b128 v[180:183], v1 offset:13824
	ds_read_b128 v[212:215], v1 offset:13888
	s_waitcnt lgkmcnt(3)
	v_mfma_f32_16x16x32_bf16 v[70:73], v[184:187], v[236:239], v[70:73]
	ds_read_b128 v[236:239], v1 offset:16128
	ds_read_b128 v[216:219], v1 offset:16192
	s_waitcnt lgkmcnt(3)
	v_mfma_f32_16x16x32_bf16 v[66:69], v[184:187], v[180:183], v[66:69]
	ds_write_b128 v173, v[10:13] offset:18432
	s_waitcnt vmcnt(14)
	ds_write_b128 v173, v[14:17] offset:27648
	global_load_dwordx4 v[10:13], v[222:223], off offset:896
	s_waitcnt lgkmcnt(3)
	v_mfma_f32_16x16x32_bf16 v[74:77], v[184:187], v[236:239], v[74:77]
	s_waitcnt vmcnt(13)
	v_mov_b64_e32 v[182:183], v[8:9]
	v_mov_b64_e32 v[186:187], v[4:5]
	v_mov_b64_e32 v[180:181], v[6:7]
	v_mov_b64_e32 v[184:185], v[2:3]
	global_load_dwordx4 v[14:17], v[224:225], off offset:896
	global_load_dwordx4 v[2:5], v[220:221], off offset:128
	global_load_dwordx4 v[6:9], v[220:221], off offset:192
	v_mfma_f32_16x16x32_bf16 v[94:97], v[176:179], v[188:191], v[94:97]
	s_waitcnt lgkmcnt(0)
	s_barrier
	v_mfma_f32_16x16x32_bf16 v[90:93], v[176:179], v[192:195], v[90:93]
	v_mfma_f32_16x16x32_bf16 v[86:89], v[176:179], v[196:199], v[86:89]
	v_mfma_f32_16x16x32_bf16 v[82:85], v[176:179], v[200:203], v[82:85]
	v_mfma_f32_16x16x32_bf16 v[78:81], v[176:179], v[204:207], v[78:81]
	v_mfma_f32_16x16x32_bf16 v[70:73], v[176:179], v[208:211], v[70:73]
	v_mfma_f32_16x16x32_bf16 v[66:69], v[176:179], v[212:215], v[66:69]
	v_mfma_f32_16x16x32_bf16 v[74:77], v[176:179], v[216:219], v[74:77]
	ds_read_b128 v[176:179], v1 offset:18432
	ds_read_b128 v[188:191], v1 offset:18496
	ds_read_b128 v[236:239], v1 offset:20736
	ds_read_b128 v[192:195], v1 offset:20800
	s_waitcnt lgkmcnt(3)
	v_mfma_f32_16x16x32_bf16 v[94:97], v[184:187], v[176:179], v[94:97]
	ds_read_b128 v[176:179], v1 offset:23040
	ds_read_b128 v[196:199], v1 offset:23104
	s_waitcnt lgkmcnt(3)
	v_mfma_f32_16x16x32_bf16 v[90:93], v[184:187], v[236:239], v[90:93]
	ds_read_b128 v[236:239], v1 offset:25344
	ds_read_b128 v[200:203], v1 offset:25408
	s_waitcnt lgkmcnt(3)
	v_mfma_f32_16x16x32_bf16 v[86:89], v[184:187], v[176:179], v[86:89]
	ds_read_b128 v[176:179], v1 offset:27648
	ds_read_b128 v[204:207], v1 offset:27712
	s_waitcnt lgkmcnt(3)
	v_mfma_f32_16x16x32_bf16 v[82:85], v[184:187], v[236:239], v[82:85]
	ds_read_b128 v[236:239], v1 offset:29952
	ds_read_b128 v[208:211], v1 offset:30016
	s_waitcnt lgkmcnt(3)
	v_mfma_f32_16x16x32_bf16 v[78:81], v[184:187], v[176:179], v[78:81]
	ds_read_b128 v[176:179], v1 offset:32256
	ds_read_b128 v[212:215], v1 offset:32320
	s_waitcnt lgkmcnt(3)
	v_mfma_f32_16x16x32_bf16 v[70:73], v[184:187], v[236:239], v[70:73]
	ds_read_b128 v[236:239], v1 offset:34560
	ds_read_b128 v[216:219], v1 offset:34624
	s_waitcnt lgkmcnt(3)
	v_mfma_f32_16x16x32_bf16 v[66:69], v[184:187], v[176:179], v[66:69]
	s_waitcnt lgkmcnt(1)
	v_mfma_f32_16x16x32_bf16 v[74:77], v[184:187], v[236:239], v[74:77]
	v_mfma_f32_16x16x32_bf16 v[94:97], v[180:183], v[188:191], v[94:97]
	v_mfma_f32_16x16x32_bf16 v[90:93], v[180:183], v[192:195], v[90:93]
	v_mfma_f32_16x16x32_bf16 v[86:89], v[180:183], v[196:199], v[86:89]
	v_mfma_f32_16x16x32_bf16 v[82:85], v[180:183], v[200:203], v[82:85]
	v_mfma_f32_16x16x32_bf16 v[78:81], v[180:183], v[204:207], v[78:81]
	v_mfma_f32_16x16x32_bf16 v[70:73], v[180:183], v[208:211], v[70:73]
	v_mfma_f32_16x16x32_bf16 v[66:69], v[180:183], v[212:215], v[66:69]
	s_waitcnt lgkmcnt(0)
	v_mfma_f32_16x16x32_bf16 v[74:77], v[180:183], v[216:219], v[74:77]
	s_cbranch_scc1 .LBB0_1114
	s_waitcnt vmcnt(13)
	ds_write_b128 v173, v[58:61]
	s_waitcnt vmcnt(12)
	ds_write_b128 v173, v[62:65] offset:9216
	s_waitcnt lgkmcnt(0)
	s_barrier
	ds_read_b128 v[58:61], v1
	ds_read_b128 v[62:65], v1 offset:64
	s_waitcnt lgkmcnt(1)
	v_mfma_f32_16x16x32_bf16 v[58:61], v[50:53], v[58:61], v[94:97]
	s_lshl_b32 s0, s2, 8
	s_bitset1_b32 s0, 7
	s_ashr_i32 s1, s0, 31
	s_waitcnt lgkmcnt(0)
	v_mfma_f32_16x16x32_bf16 v[58:61], v[54:57], v[62:65], v[58:61]
	ds_read_b128 v[62:65], v1 offset:2304
	ds_read_b128 v[94:97], v1 offset:2368
	s_lshl_b64 s[0:1], s[0:1], 11
	s_add_u32 s0, s46, s0
	s_waitcnt lgkmcnt(1)
	v_mfma_f32_16x16x32_bf16 v[62:65], v[50:53], v[62:65], v[90:93]
	s_addc_u32 s1, s47, s1
	s_lshl_b32 s2, s14, 1
	s_add_u32 s14, s0, s2
	s_waitcnt lgkmcnt(0)
	v_mfma_f32_16x16x32_bf16 v[62:65], v[54:57], v[94:97], v[62:65]
	ds_read_b128 v[90:93], v1 offset:4608
	ds_read_b128 v[94:97], v1 offset:4672
	s_addc_u32 s15, s1, 0
	s_waitcnt lgkmcnt(1)
	v_mfma_f32_16x16x32_bf16 v[86:89], v[50:53], v[90:93], v[86:89]
	s_waitcnt lgkmcnt(0)
	v_mfma_f32_16x16x32_bf16 v[86:89], v[54:57], v[94:97], v[86:89]
	ds_read_b128 v[90:93], v1 offset:6912
	ds_read_b128 v[94:97], v1 offset:6976
	s_waitcnt lgkmcnt(1)
	v_mfma_f32_16x16x32_bf16 v[82:85], v[50:53], v[90:93], v[82:85]
	s_waitcnt lgkmcnt(0)
	v_mfma_f32_16x16x32_bf16 v[82:85], v[54:57], v[94:97], v[82:85]
	ds_read_b128 v[90:93], v1 offset:9216
	ds_read_b128 v[94:97], v1 offset:9280
	s_waitcnt lgkmcnt(1)
	v_mfma_f32_16x16x32_bf16 v[78:81], v[50:53], v[90:93], v[78:81]
	s_waitcnt lgkmcnt(0)
	v_mfma_f32_16x16x32_bf16 v[78:81], v[54:57], v[94:97], v[78:81]
	ds_read_b128 v[90:93], v1 offset:11520
	ds_read_b128 v[94:97], v1 offset:11584
	s_waitcnt lgkmcnt(1)
	v_mfma_f32_16x16x32_bf16 v[70:73], v[50:53], v[90:93], v[70:73]
	s_waitcnt lgkmcnt(0)
	v_mfma_f32_16x16x32_bf16 v[70:73], v[54:57], v[94:97], v[70:73]
	ds_read_b128 v[90:93], v1 offset:13824
	ds_read_b128 v[94:97], v1 offset:13888
	s_waitcnt lgkmcnt(1)
	v_mfma_f32_16x16x32_bf16 v[66:69], v[50:53], v[90:93], v[66:69]
	s_waitcnt lgkmcnt(0)
	v_mfma_f32_16x16x32_bf16 v[66:69], v[54:57], v[94:97], v[66:69]
	ds_read_b128 v[90:93], v1 offset:16128
	ds_read_b128 v[94:97], v1 offset:16192
	s_waitcnt vmcnt(11)
	ds_write_b128 v173, v[46:49] offset:18432
	s_waitcnt vmcnt(10)
	ds_write_b128 v173, v[42:45] offset:27648
	s_waitcnt lgkmcnt(0)
	s_barrier
	ds_read_b128 v[42:45], v1 offset:18432
	ds_read_b128 v[46:49], v1 offset:18496
	v_mfma_f32_16x16x32_bf16 v[50:53], v[50:53], v[90:93], v[74:77]
	s_waitcnt vmcnt(9) lgkmcnt(1)
	v_mfma_f32_16x16x32_bf16 v[42:45], v[34:37], v[42:45], v[58:61]
	v_mfma_f32_16x16x32_bf16 v[50:53], v[54:57], v[94:97], v[50:53]
	s_waitcnt vmcnt(8) lgkmcnt(0)
	v_mfma_f32_16x16x32_bf16 v[42:45], v[38:41], v[46:49], v[42:45]
	ds_read_b128 v[46:49], v1 offset:20736
	ds_read_b128 v[54:57], v1 offset:20800
	s_waitcnt lgkmcnt(1)
	v_mfma_f32_16x16x32_bf16 v[46:49], v[34:37], v[46:49], v[62:65]
	s_waitcnt lgkmcnt(0)
	v_mfma_f32_16x16x32_bf16 v[46:49], v[38:41], v[54:57], v[46:49]
	ds_read_b128 v[54:57], v1 offset:23040
	ds_read_b128 v[58:61], v1 offset:23104
	s_waitcnt lgkmcnt(1)
	v_mfma_f32_16x16x32_bf16 v[54:57], v[34:37], v[54:57], v[86:89]
	s_waitcnt lgkmcnt(0)
	v_mfma_f32_16x16x32_bf16 v[54:57], v[38:41], v[58:61], v[54:57]
	ds_read_b128 v[58:61], v1 offset:25344
	ds_read_b128 v[62:65], v1 offset:25408
	s_waitcnt lgkmcnt(1)
	v_mfma_f32_16x16x32_bf16 v[58:61], v[34:37], v[58:61], v[82:85]
	s_waitcnt lgkmcnt(0)
	v_mfma_f32_16x16x32_bf16 v[58:61], v[38:41], v[62:65], v[58:61]
	ds_read_b128 v[62:65], v1 offset:27648
	ds_read_b128 v[74:77], v1 offset:27712
	s_waitcnt lgkmcnt(1)
	v_mfma_f32_16x16x32_bf16 v[62:65], v[34:37], v[62:65], v[78:81]
	s_waitcnt lgkmcnt(0)
	v_mfma_f32_16x16x32_bf16 v[62:65], v[38:41], v[74:77], v[62:65]
	ds_read_b128 v[74:77], v1 offset:29952
	ds_read_b128 v[78:81], v1 offset:30016
	s_waitcnt lgkmcnt(1)
	v_mfma_f32_16x16x32_bf16 v[70:73], v[34:37], v[74:77], v[70:73]
	s_waitcnt lgkmcnt(0)
	v_mfma_f32_16x16x32_bf16 v[70:73], v[38:41], v[78:81], v[70:73]
	ds_read_b128 v[74:77], v1 offset:32256
	ds_read_b128 v[78:81], v1 offset:32320
	s_waitcnt lgkmcnt(1)
	v_mfma_f32_16x16x32_bf16 v[66:69], v[34:37], v[74:77], v[66:69]
	s_waitcnt lgkmcnt(0)
	v_mfma_f32_16x16x32_bf16 v[66:69], v[38:41], v[78:81], v[66:69]
	ds_read_b128 v[74:77], v1 offset:34560
	ds_read_b128 v[78:81], v1 offset:34624
	s_waitcnt vmcnt(7)
	ds_write_b128 v173, v[26:29]
	s_waitcnt vmcnt(6)
	ds_write_b128 v173, v[30:33] offset:9216
	s_waitcnt lgkmcnt(0)
	s_barrier
	ds_read_b128 v[26:29], v1
	ds_read_b128 v[30:33], v1 offset:64
	v_mfma_f32_16x16x32_bf16 v[34:37], v[34:37], v[74:77], v[50:53]
	v_lshl_add_u64 v[74:75], s[14:15], 0, v[98:99]
	s_waitcnt vmcnt(5) lgkmcnt(1)
	v_mfma_f32_16x16x32_bf16 v[26:29], v[18:21], v[26:29], v[42:45]
	v_mfma_f32_16x16x32_bf16 v[34:37], v[38:41], v[78:81], v[34:37]
	v_lshl_add_u64 v[78:79], v[74:75], 0, v[124:125]
	s_waitcnt vmcnt(4) lgkmcnt(0)
	v_mfma_f32_16x16x32_bf16 v[26:29], v[22:25], v[30:33], v[26:29]
	ds_read_b128 v[30:33], v1 offset:2304
	ds_read_b128 v[38:41], v1 offset:2368
	s_waitcnt lgkmcnt(1)
	v_mfma_f32_16x16x32_bf16 v[30:33], v[18:21], v[30:33], v[46:49]
	s_waitcnt lgkmcnt(0)
	v_mfma_f32_16x16x32_bf16 v[30:33], v[22:25], v[38:41], v[30:33]
	ds_read_b128 v[38:41], v1 offset:4608
	ds_read_b128 v[42:45], v1 offset:4672
	s_waitcnt lgkmcnt(1)
	v_mfma_f32_16x16x32_bf16 v[38:41], v[18:21], v[38:41], v[54:57]
	s_waitcnt lgkmcnt(0)
	v_mfma_f32_16x16x32_bf16 v[38:41], v[22:25], v[42:45], v[38:41]
	ds_read_b128 v[42:45], v1 offset:6912
	ds_read_b128 v[46:49], v1 offset:6976
	s_waitcnt lgkmcnt(1)
	v_mfma_f32_16x16x32_bf16 v[42:45], v[18:21], v[42:45], v[58:61]
	s_waitcnt lgkmcnt(0)
	v_mfma_f32_16x16x32_bf16 v[42:45], v[22:25], v[46:49], v[42:45]
	ds_read_b128 v[46:49], v1 offset:9216
	ds_read_b128 v[50:53], v1 offset:9280
	s_waitcnt lgkmcnt(1)
	v_mfma_f32_16x16x32_bf16 v[46:49], v[18:21], v[46:49], v[62:65]
	s_waitcnt lgkmcnt(0)
	v_mfma_f32_16x16x32_bf16 v[46:49], v[22:25], v[50:53], v[46:49]
	ds_read_b128 v[50:53], v1 offset:11520
	ds_read_b128 v[54:57], v1 offset:11584
	s_waitcnt lgkmcnt(1)
	v_mfma_f32_16x16x32_bf16 v[50:53], v[18:21], v[50:53], v[70:73]
	s_waitcnt lgkmcnt(0)
	v_mfma_f32_16x16x32_bf16 v[50:53], v[22:25], v[54:57], v[50:53]
	ds_read_b128 v[54:57], v1 offset:13824
	ds_read_b128 v[58:61], v1 offset:13888
	s_waitcnt lgkmcnt(1)
	v_mfma_f32_16x16x32_bf16 v[54:57], v[18:21], v[54:57], v[66:69]
	s_nop 2
	v_lshl_add_u64 v[66:67], v[74:75], 0, v[122:123]
	s_waitcnt lgkmcnt(0)
	v_mfma_f32_16x16x32_bf16 v[54:57], v[22:25], v[58:61], v[54:57]
	ds_read_b128 v[58:61], v1 offset:16128
	ds_read_b128 v[62:65], v1 offset:16192
	s_waitcnt vmcnt(3)
	ds_write_b128 v173, v[10:13] offset:18432
	s_waitcnt vmcnt(2)
	ds_write_b128 v173, v[14:17] offset:27648
	s_waitcnt lgkmcnt(0)
	s_barrier
	ds_read_b128 v[10:13], v1 offset:18432
	ds_read_b128 v[14:17], v1 offset:18496
	s_waitcnt vmcnt(1) lgkmcnt(1)
	v_mfma_f32_16x16x32_bf16 v[10:13], v[2:5], v[10:13], v[26:29]
	v_mfma_f32_16x16x32_bf16 v[18:21], v[18:21], v[58:61], v[34:37]
	s_waitcnt vmcnt(0) lgkmcnt(0)
	v_mfma_f32_16x16x32_bf16 v[34:37], v[6:9], v[14:17], v[10:13]
	s_nop 4
	ds_read_b128 v[10:13], v1 offset:20736
	ds_read_b128 v[14:17], v1 offset:20800
	s_waitcnt lgkmcnt(1)
	v_mfma_f32_16x16x32_bf16 v[10:13], v[2:5], v[10:13], v[30:33]
	s_waitcnt lgkmcnt(0)
	v_mfma_f32_16x16x32_bf16 v[30:33], v[6:9], v[14:17], v[10:13]
	s_nop 5
	ds_read_b128 v[10:13], v1 offset:23040
	ds_read_b128 v[14:17], v1 offset:23104
	s_waitcnt lgkmcnt(1)
	v_mfma_f32_16x16x32_bf16 v[10:13], v[2:5], v[10:13], v[38:41]
	s_waitcnt lgkmcnt(0)
	v_mfma_f32_16x16x32_bf16 v[26:29], v[6:9], v[14:17], v[10:13]
	s_nop 5
	ds_read_b128 v[10:13], v1 offset:25344
	ds_read_b128 v[14:17], v1 offset:25408
	s_waitcnt lgkmcnt(1)
	v_mfma_f32_16x16x32_bf16 v[10:13], v[2:5], v[10:13], v[42:45]
	v_mfma_f32_16x16x32_bf16 v[58:61], v[22:25], v[62:65], v[18:21]
	v_lshl_add_u64 v[62:63], v[74:75], 0, v[120:121]
	s_waitcnt lgkmcnt(0)
	v_mfma_f32_16x16x32_bf16 v[22:25], v[6:9], v[14:17], v[10:13]
	s_nop 3
	ds_read_b128 v[10:13], v1 offset:27648
	ds_read_b128 v[14:17], v1 offset:27712
	s_waitcnt lgkmcnt(1)
	v_mfma_f32_16x16x32_bf16 v[10:13], v[2:5], v[10:13], v[46:49]
	s_nop 2
	v_lshl_add_u64 v[46:47], v[74:75], 0, v[116:117]
	s_waitcnt lgkmcnt(0)
	v_mfma_f32_16x16x32_bf16 v[18:21], v[6:9], v[14:17], v[10:13]
	s_nop 2
	ds_read_b128 v[10:13], v1 offset:29952
	ds_read_b128 v[14:17], v1 offset:30016
	s_waitcnt lgkmcnt(1)
	v_mfma_f32_16x16x32_bf16 v[10:13], v[2:5], v[10:13], v[50:53]
	s_waitcnt lgkmcnt(0)
	v_mfma_f32_16x16x32_bf16 v[14:17], v[6:9], v[14:17], v[10:13]
	s_nop 5
	ds_read_b128 v[10:13], v1 offset:32256
	ds_read_b128 v[38:41], v1 offset:32320
	s_waitcnt lgkmcnt(1)
	v_mfma_f32_16x16x32_bf16 v[10:13], v[2:5], v[10:13], v[54:57]
	s_nop 2
	v_lshl_add_u64 v[54:55], v[74:75], 0, v[118:119]
	s_waitcnt lgkmcnt(0)
	v_mfma_f32_16x16x32_bf16 v[10:13], v[6:9], v[38:41], v[10:13]
	ds_read_b128 v[38:41], v1 offset:34560
	ds_read_b128 v[42:45], v1 offset:34624
	s_waitcnt lgkmcnt(1)
	v_mfma_f32_16x16x32_bf16 v[2:5], v[2:5], v[38:41], v[58:61]
	v_mov_b64_e32 v[38:39], s[10:11]
	s_waitcnt lgkmcnt(0)
	v_mfma_f32_16x16x32_bf16 v[2:5], v[6:9], v[42:45], v[2:5]
	v_lshl_add_u64 v[6:7], s[12:13], 2, v[126:127]
	global_load_dwordx4 v[6:9], v[6:7], off
	v_lshl_add_u64 v[42:43], v[74:75], 0, v[112:113]
	s_waitcnt vmcnt(0)
	v_pk_fma_f32 v[6:7], v[6:7], s[8:9], v[38:39] op_sel_hi:[1,0,0]
	s_nop 0
	v_mul_f32_e32 v40, 0x4b800000, v6
	v_cmp_gt_f32_e64 s[0:1], s20, v6
	v_cmp_gt_f32_e32 vcc, s20, v7
	s_nop 0
	v_cndmask_b32_e64 v6, v6, v40, s[0:1]
	v_rsq_f32_e32 v6, v6
	s_nop 0
	v_mul_f32_e32 v40, 0x45800000, v6
	v_cndmask_b32_e64 v40, v6, v40, s[0:1]
	v_mul_f32_e32 v6, 0x4b800000, v7
	v_cndmask_b32_e32 v6, v7, v6, vcc
	v_rsq_f32_e32 v6, v6
	v_mul_f32_e32 v2, v2, v40
	v_mul_f32_e32 v7, 0x45800000, v6
	v_cndmask_b32_e32 v41, v6, v7, vcc
	v_pk_fma_f32 v[6:7], v[8:9], s[8:9], v[38:39] op_sel_hi:[1,0,0]
	v_lshl_add_u64 v[38:39], v[74:75], 0, v[114:115]
	v_mul_f32_e32 v8, 0x4b800000, v6
	v_cmp_gt_f32_e64 s[0:1], s20, v6
	v_cmp_gt_f32_e32 vcc, s20, v7
	s_nop 0
	v_cndmask_b32_e64 v6, v6, v8, s[0:1]
	v_rsq_f32_e32 v6, v6
	s_nop 0
	v_mul_f32_e32 v8, 0x45800000, v6
	v_cndmask_b32_e64 v6, v6, v8, s[0:1]
	v_mul_f32_e32 v8, 0x4b800000, v7
	v_cndmask_b32_e32 v7, v7, v8, vcc
	v_rsq_f32_e32 v7, v7
	s_lshl_b64 s[0:1], s[12:13], 10
	s_add_u32 s0, s56, s0
	s_addc_u32 s1, s57, s1
	v_mul_f32_e32 v8, 0x45800000, v7
	v_cndmask_b32_e32 v7, v7, v8, vcc
	v_mul_f32_e32 v8, v34, v40
	v_cvt_pk_bf16_f32 v8, v8, v99
	ds_write_b16 v163, v8 offset:36864
	v_mul_f32_e32 v8, v35, v41
	v_cvt_pk_bf16_f32 v8, v8, v99
	ds_write_b16 v163, v8 offset:37136
	v_mul_f32_e32 v8, v36, v6
	v_cvt_pk_bf16_f32 v8, v8, v99
	ds_write_b16 v163, v8 offset:37408
	v_mul_f32_e32 v8, v37, v7
	v_cvt_pk_bf16_f32 v8, v8, v99
	ds_write_b16 v163, v8 offset:37680
	v_mul_f32_e32 v8, v30, v40
	v_cvt_pk_bf16_f32 v8, v8, v99
	ds_write_b16 v163, v8 offset:36896
	v_mul_f32_e32 v8, v31, v41
	v_cvt_pk_bf16_f32 v8, v8, v99
	ds_write_b16 v163, v8 offset:37168
	v_mul_f32_e32 v8, v32, v6
	v_cvt_pk_bf16_f32 v8, v8, v99
	ds_write_b16 v163, v8 offset:37440
	v_mul_f32_e32 v8, v33, v7
	v_cvt_pk_bf16_f32 v8, v8, v99
	ds_write_b16 v163, v8 offset:37712
	v_mul_f32_e32 v8, v26, v40
	v_cvt_pk_bf16_f32 v8, v8, v99
	ds_write_b16 v163, v8 offset:36928
	v_mul_f32_e32 v8, v27, v41
	v_cvt_pk_bf16_f32 v8, v8, v99
	ds_write_b16 v163, v8 offset:37200
	v_mul_f32_e32 v8, v28, v6
	v_cvt_pk_bf16_f32 v8, v8, v99
	ds_write_b16 v163, v8 offset:37472
	v_mul_f32_e32 v8, v29, v7
	v_cvt_pk_bf16_f32 v8, v8, v99
	ds_write_b16 v163, v8 offset:37744
	v_mul_f32_e32 v8, v22, v40
	v_cvt_pk_bf16_f32 v8, v8, v99
	ds_write_b16 v163, v8 offset:36960
	v_mul_f32_e32 v8, v23, v41
	v_cvt_pk_bf16_f32 v8, v8, v99
	ds_write_b16 v163, v8 offset:37232
	v_mul_f32_e32 v8, v24, v6
	v_cvt_pk_bf16_f32 v8, v8, v99
	ds_write_b16 v163, v8 offset:37504
	v_mul_f32_e32 v8, v25, v7
	v_cvt_pk_bf16_f32 v8, v8, v99
	ds_write_b16 v163, v8 offset:37776
	v_mul_f32_e32 v8, v18, v40
	v_cvt_pk_bf16_f32 v8, v8, v99
	ds_write_b16 v163, v8 offset:36992
	v_mul_f32_e32 v8, v19, v41
	v_cvt_pk_bf16_f32 v8, v8, v99
	ds_write_b16 v163, v8 offset:37264
	v_mul_f32_e32 v8, v20, v6
	v_cvt_pk_bf16_f32 v8, v8, v99
	ds_write_b16 v163, v8 offset:37536
	v_mul_f32_e32 v8, v21, v7
	v_cvt_pk_bf16_f32 v8, v8, v99
	ds_write_b16 v163, v8 offset:37808
	v_mul_f32_e32 v8, v14, v40
	v_cvt_pk_bf16_f32 v8, v8, v99
	ds_write_b16 v163, v8 offset:37024
	v_mul_f32_e32 v8, v15, v41
	v_cvt_pk_bf16_f32 v8, v8, v99
	ds_write_b16 v163, v8 offset:37296
	v_mul_f32_e32 v8, v16, v6
	v_cvt_pk_bf16_f32 v8, v8, v99
	ds_write_b16 v163, v8 offset:37568
	v_mul_f32_e32 v8, v17, v7
	v_cvt_pk_bf16_f32 v8, v8, v99
	ds_write_b16 v163, v8 offset:37840
	v_mul_f32_e32 v8, v10, v40
	v_cvt_pk_bf16_f32 v8, v8, v99
	ds_write_b16 v163, v8 offset:37056
	v_mul_f32_e32 v8, v11, v41
	v_cvt_pk_bf16_f32 v8, v8, v99
	ds_write_b16 v163, v8 offset:37328
	v_mul_f32_e32 v8, v12, v6
	v_cvt_pk_bf16_f32 v8, v8, v99
	ds_write_b16 v163, v8 offset:37600
	v_mul_f32_e32 v8, v13, v7
	v_cvt_pk_bf16_f32 v8, v8, v99
	ds_write_b16 v163, v8 offset:37872
	v_cvt_pk_bf16_f32 v2, v2, v99
	ds_write_b16 v163, v2 offset:37088
	v_mul_f32_e32 v2, v3, v41
	v_cvt_pk_bf16_f32 v2, v2, v99
	ds_write_b16 v163, v2 offset:37360
	v_mul_f32_e32 v2, v4, v6
	v_cvt_pk_bf16_f32 v2, v2, v99
	ds_write_b16 v163, v2 offset:37632
	v_mul_f32_e32 v2, v5, v7
	v_add_co_u32_e32 v38, vcc, s21, v38
	v_cvt_pk_bf16_f32 v2, v2, v99
	ds_write_b16 v163, v2 offset:37904
	s_nop 0
	v_addc_co_u32_e32 v39, vcc, -1, v39, vcc
	s_waitcnt lgkmcnt(0)
	s_barrier
	ds_read_b128 v[14:17], v164 offset:36864
	ds_read_b128 v[10:13], v164 offset:36928
	ds_read_b128 v[6:9], v164 offset:36992
	ds_read_b128 v[2:5], v164 offset:37056
	v_lshl_add_u64 v[18:19], v[74:75], 0, v[104:105]
	global_load_dwordx4 v[34:37], v[42:43], off
	v_lshl_add_u64 v[22:23], v[74:75], 0, v[106:107]
	global_load_dwordx4 v[38:41], v[38:39], off
	v_add_co_u32_e32 v42, vcc, s22, v42
	global_load_dwordx4 v[18:21], v[18:19], off
	v_lshl_add_u64 v[26:27], v[74:75], 0, v[108:109]
	v_lshl_add_u64 v[30:31], v[74:75], 0, v[110:111]
	v_addc_co_u32_e32 v43, vcc, 0, v43, vcc
	global_load_dwordx4 v[22:25], v[22:23], off
	v_add_co_u32_e32 v70, vcc, s23, v66
	global_load_dwordx4 v[26:29], v[26:27], off
	s_nop 0
	v_addc_co_u32_e32 v71, vcc, -1, v67, vcc
	global_load_dwordx4 v[30:33], v[30:31], off
	s_add_u32 s0, s0, s2
	global_load_dwordx4 v[42:45], v[42:43], off
	s_addc_u32 s1, s1, 0
	global_load_dwordx4 v[46:49], v[46:47], off
	s_nop 0
	global_load_dwordx4 v[50:53], v[54:55], off offset:1024
	s_nop 0
	global_load_dwordx4 v[54:57], v[54:55], off offset:3072
	s_nop 0
	global_load_dwordx4 v[58:61], v[62:63], off offset:1024
	s_nop 0
	global_load_dwordx4 v[62:65], v[62:63], off offset:3072
	s_nop 0
	global_load_dwordx4 v[66:69], v[70:71], off offset:-3072
	s_nop 0
	global_load_dwordx4 v[70:73], v[70:71], off offset:-1024
	s_nop 0
	global_load_dwordx4 v[74:77], v[78:79], off offset:1024
	s_nop 0
	global_load_dwordx4 v[78:81], v[78:79], off offset:3072
	s_waitcnt lgkmcnt(0)
	s_barrier
	s_waitcnt vmcnt(13)
	ds_write_b128 v166, v[18:21]
	s_waitcnt vmcnt(12)
	ds_write_b128 v167, v[22:25]
	s_waitcnt vmcnt(11)
	ds_write_b128 v168, v[26:29]
	s_waitcnt vmcnt(10)
	ds_write_b128 v169, v[30:33]
	ds_write_b128 v166, v[34:37] offset:34816
	ds_write_b128 v170, v[38:41]
	s_waitcnt vmcnt(9)
	ds_write_b128 v166, v[42:45] offset:52224
	s_waitcnt vmcnt(8)
	ds_write_b128 v171, v[46:49]
	v_add_u32_e32 v20, 0x400, v140
	s_add_i32 s27, s27, s88
	s_add_i32 s3, s3, s9
	s_add_i32 s11, s11, s16
	s_cmpk_lt_i32 s27, 0x100
	s_waitcnt vmcnt(7)
	v_and_b32_e32 v18, 0xffff, v50
	v_lshrrev_b32_e32 v19, 16, v50
	s_waitcnt vmcnt(6)
	v_lshl_or_b32 v18, v54, 16, v18
	v_and_or_b32 v19, v54, s24, v19
	ds_write2_b32 v140, v18, v19 offset1:132
	v_and_b32_e32 v18, 0xffff, v51
	v_lshrrev_b32_e32 v19, 16, v51
	v_lshl_or_b32 v18, v55, 16, v18
	v_and_or_b32 v19, v55, s24, v19
	ds_write2_b32 v20, v18, v19 offset0:8 offset1:140
	v_and_b32_e32 v18, 0xffff, v52
	v_lshrrev_b32_e32 v19, 16, v52
	v_lshl_or_b32 v18, v56, 16, v18
	v_and_or_b32 v19, v56, s24, v19
	v_add_u32_e32 v20, 0x800, v140
	ds_write2_b32 v20, v18, v19 offset0:16 offset1:148
	v_and_b32_e32 v18, 0xffff, v53
	v_lshrrev_b32_e32 v19, 16, v53
	v_lshl_or_b32 v18, v57, 16, v18
	v_and_or_b32 v19, v57, s24, v19
	v_add_u32_e32 v20, 0xc00, v140
	ds_write2_b32 v20, v18, v19 offset0:24 offset1:156
	s_waitcnt vmcnt(5)
	v_and_b32_e32 v18, 0xffff, v58
	v_lshrrev_b32_e32 v19, 16, v58
	s_waitcnt vmcnt(4)
	v_lshl_or_b32 v18, v62, 16, v18
	v_and_or_b32 v19, v62, s24, v19
	ds_write2_b32 v141, v18, v19 offset1:132
	v_and_b32_e32 v18, 0xffff, v59
	v_lshrrev_b32_e32 v19, 16, v59
	v_lshl_or_b32 v18, v63, 16, v18
	v_and_or_b32 v19, v63, s24, v19
	v_add_u32_e32 v20, 0x400, v141
	ds_write2_b32 v20, v18, v19 offset0:8 offset1:140
	v_and_b32_e32 v18, 0xffff, v60
	v_lshrrev_b32_e32 v19, 16, v60
	v_lshl_or_b32 v18, v64, 16, v18
	v_and_or_b32 v19, v64, s24, v19
	v_add_u32_e32 v20, 0x800, v141
	ds_write2_b32 v20, v18, v19 offset0:16 offset1:148
	v_and_b32_e32 v18, 0xffff, v61
	v_lshrrev_b32_e32 v19, 16, v61
	v_lshl_or_b32 v18, v65, 16, v18
	v_and_or_b32 v19, v65, s24, v19
	v_add_u32_e32 v20, 0xc00, v141
	ds_write2_b32 v20, v18, v19 offset0:24 offset1:156
	s_waitcnt vmcnt(3)
	v_and_b32_e32 v18, 0xffff, v66
	v_lshrrev_b32_e32 v19, 16, v66
	s_waitcnt vmcnt(2)
	v_lshl_or_b32 v18, v70, 16, v18
	v_and_or_b32 v19, v70, s24, v19
	ds_write2_b32 v142, v18, v19 offset1:132
	v_and_b32_e32 v18, 0xffff, v67
	v_lshrrev_b32_e32 v19, 16, v67
	v_lshl_or_b32 v18, v71, 16, v18
	v_and_or_b32 v19, v71, s24, v19
	v_add_u32_e32 v20, 0x400, v142
	ds_write2_b32 v20, v18, v19 offset0:8 offset1:140
	v_and_b32_e32 v18, 0xffff, v68
	v_lshrrev_b32_e32 v19, 16, v68
	v_lshl_or_b32 v18, v72, 16, v18
	v_and_or_b32 v19, v72, s24, v19
	v_add_u32_e32 v20, 0x800, v142
	ds_write2_b32 v20, v18, v19 offset0:16 offset1:148
	v_and_b32_e32 v18, 0xffff, v69
	v_lshrrev_b32_e32 v19, 16, v69
	v_lshl_or_b32 v18, v73, 16, v18
	v_and_or_b32 v19, v73, s24, v19
	v_add_u32_e32 v20, 0xc00, v142
	ds_write2_b32 v20, v18, v19 offset0:24 offset1:156
	s_waitcnt vmcnt(1)
	v_and_b32_e32 v18, 0xffff, v74
	v_lshrrev_b32_e32 v19, 16, v74
	s_waitcnt vmcnt(0)
	v_lshl_or_b32 v18, v78, 16, v18
	v_and_or_b32 v19, v78, s24, v19
	ds_write2_b32 v143, v18, v19 offset1:132
	v_and_b32_e32 v18, 0xffff, v75
	v_lshrrev_b32_e32 v19, 16, v75
	v_lshl_or_b32 v18, v79, 16, v18
	v_and_or_b32 v19, v79, s24, v19
	v_add_u32_e32 v20, 0x400, v143
	ds_write2_b32 v20, v18, v19 offset0:8 offset1:140
	v_and_b32_e32 v18, 0xffff, v76
	v_lshrrev_b32_e32 v19, 16, v76
	v_lshl_or_b32 v18, v80, 16, v18
	v_and_or_b32 v19, v80, s24, v19
	v_add_u32_e32 v20, 0x800, v143
	ds_write2_b32 v20, v18, v19 offset0:16 offset1:148
	v_and_b32_e32 v18, 0xffff, v77
	v_lshrrev_b32_e32 v19, 16, v77
	v_lshl_or_b32 v18, v81, 16, v18
	v_and_or_b32 v19, v81, s24, v19
	v_add_u32_e32 v20, 0xc00, v143
	ds_write2_b32 v20, v18, v19 offset0:24 offset1:156
	s_waitcnt lgkmcnt(0)
	s_barrier
	ds_read_b128 v[18:21], v172
	ds_read_b128 v[22:25], v172 offset:64
	s_waitcnt lgkmcnt(1)
	v_mfma_f32_16x16x32_bf16 v[18:21], v[18:21], v[14:17], 0
	ds_read_b128 v[26:29], v172 offset:4416
	s_waitcnt lgkmcnt(1)
	v_mfma_f32_16x16x32_bf16 v[18:21], v[22:25], v[10:13], v[18:21]
	ds_read_b128 v[22:25], v172 offset:128
	s_waitcnt lgkmcnt(0)
	v_mfma_f32_16x16x32_bf16 v[18:21], v[22:25], v[6:9], v[18:21]
	ds_read_b128 v[22:25], v172 offset:192
	s_waitcnt lgkmcnt(0)
	v_mfma_f32_16x16x32_bf16 v[18:21], v[22:25], v[2:5], v[18:21]
	s_nop 7
	v_mul_f32_e32 v22, 0x3db504f3, v18
	v_mul_f32_e32 v23, 0x3db504f3, v19
	v_max3_f32 v22, v22, s26, v23
	v_mul_f32_e32 v23, 0x3db504f3, v20
	v_mul_f32_e32 v24, 0x3db504f3, v21
	v_max3_f32 v30, v22, v23, v24
	ds_read_b128 v[22:25], v172 offset:4352
	s_waitcnt lgkmcnt(0)
	v_mfma_f32_16x16x32_bf16 v[22:25], v[22:25], v[14:17], 0
	v_mfma_f32_16x16x32_bf16 v[22:25], v[26:29], v[10:13], v[22:25]
	ds_read_b128 v[26:29], v172 offset:4480
	s_waitcnt lgkmcnt(0)
	v_mfma_f32_16x16x32_bf16 v[22:25], v[26:29], v[6:9], v[22:25]
	ds_read_b128 v[26:29], v172 offset:4544
	s_waitcnt lgkmcnt(0)
	v_mfma_f32_16x16x32_bf16 v[22:25], v[26:29], v[2:5], v[22:25]
	s_nop 7
	v_mul_f32_e32 v26, 0x3db504f3, v22
	v_mul_f32_e32 v27, 0x3db504f3, v23
	v_max3_f32 v26, v30, v26, v27
	v_mul_f32_e32 v27, 0x3db504f3, v24
	v_mul_f32_e32 v28, 0x3db504f3, v25
	v_max3_f32 v34, v26, v27, v28
	ds_read_b128 v[26:29], v172 offset:8704
	ds_read_b128 v[30:33], v172 offset:8768
	s_waitcnt lgkmcnt(1)
	v_mfma_f32_16x16x32_bf16 v[26:29], v[26:29], v[14:17], 0
	s_waitcnt lgkmcnt(0)
	v_mfma_f32_16x16x32_bf16 v[26:29], v[30:33], v[10:13], v[26:29]
	ds_read_b128 v[30:33], v172 offset:8832
	s_waitcnt lgkmcnt(0)
	v_mfma_f32_16x16x32_bf16 v[26:29], v[30:33], v[6:9], v[26:29]
	ds_read_b128 v[30:33], v172 offset:8896
	s_waitcnt lgkmcnt(0)
	v_mfma_f32_16x16x32_bf16 v[26:29], v[30:33], v[2:5], v[26:29]
	s_nop 7
	v_mul_f32_e32 v30, 0x3db504f3, v26
	v_mul_f32_e32 v31, 0x3db504f3, v27
	v_max3_f32 v30, v34, v30, v31
	v_mul_f32_e32 v31, 0x3db504f3, v28
	v_mul_f32_e32 v32, 0x3db504f3, v29
	v_max3_f32 v38, v30, v31, v32
	ds_read_b128 v[30:33], v172 offset:13056
	ds_read_b128 v[34:37], v172 offset:13120
	s_waitcnt lgkmcnt(1)
	v_mfma_f32_16x16x32_bf16 v[30:33], v[30:33], v[14:17], 0
	s_waitcnt lgkmcnt(0)
	v_mfma_f32_16x16x32_bf16 v[30:33], v[34:37], v[10:13], v[30:33]
	ds_read_b128 v[34:37], v172 offset:13184
	s_waitcnt lgkmcnt(0)
	v_mfma_f32_16x16x32_bf16 v[30:33], v[34:37], v[6:9], v[30:33]
	ds_read_b128 v[34:37], v172 offset:13248
	s_waitcnt lgkmcnt(0)
	v_mfma_f32_16x16x32_bf16 v[30:33], v[34:37], v[2:5], v[30:33]
	s_nop 7
	v_mul_f32_e32 v34, 0x3db504f3, v30
	v_mul_f32_e32 v35, 0x3db504f3, v31
	v_max3_f32 v34, v38, v34, v35
	v_mul_f32_e32 v35, 0x3db504f3, v32
	v_mul_f32_e32 v36, 0x3db504f3, v33
	v_max3_f32 v42, v34, v35, v36
	ds_read_b128 v[34:37], v172 offset:17408
	ds_read_b128 v[38:41], v172 offset:17472
	s_waitcnt lgkmcnt(1)
	v_mfma_f32_16x16x32_bf16 v[34:37], v[34:37], v[14:17], 0
	s_waitcnt lgkmcnt(0)
	v_mfma_f32_16x16x32_bf16 v[34:37], v[38:41], v[10:13], v[34:37]
	ds_read_b128 v[38:41], v172 offset:17536
	s_waitcnt lgkmcnt(0)
	v_mfma_f32_16x16x32_bf16 v[34:37], v[38:41], v[6:9], v[34:37]
	ds_read_b128 v[38:41], v172 offset:17600
	s_waitcnt lgkmcnt(0)
	v_mfma_f32_16x16x32_bf16 v[34:37], v[38:41], v[2:5], v[34:37]
	s_nop 7
	v_mul_f32_e32 v38, 0x3db504f3, v34
	v_mul_f32_e32 v39, 0x3db504f3, v35
	v_max3_f32 v38, v42, v38, v39
	v_mul_f32_e32 v39, 0x3db504f3, v36
	v_mul_f32_e32 v40, 0x3db504f3, v37
	v_max3_f32 v46, v38, v39, v40
	ds_read_b128 v[38:41], v172 offset:21760
	ds_read_b128 v[42:45], v172 offset:21824
	s_waitcnt lgkmcnt(1)
	v_mfma_f32_16x16x32_bf16 v[38:41], v[38:41], v[14:17], 0
	s_waitcnt lgkmcnt(0)
	v_mfma_f32_16x16x32_bf16 v[38:41], v[42:45], v[10:13], v[38:41]
	ds_read_b128 v[42:45], v172 offset:21888
	s_waitcnt lgkmcnt(0)
	v_mfma_f32_16x16x32_bf16 v[38:41], v[42:45], v[6:9], v[38:41]
	ds_read_b128 v[42:45], v172 offset:21952
	s_waitcnt lgkmcnt(0)
	v_mfma_f32_16x16x32_bf16 v[38:41], v[42:45], v[2:5], v[38:41]
	s_nop 7
	v_mul_f32_e32 v42, 0x3db504f3, v38
	v_mul_f32_e32 v43, 0x3db504f3, v39
	v_max3_f32 v42, v46, v42, v43
	v_mul_f32_e32 v43, 0x3db504f3, v40
	v_mul_f32_e32 v44, 0x3db504f3, v41
	v_max3_f32 v50, v42, v43, v44
	ds_read_b128 v[42:45], v172 offset:26112
	ds_read_b128 v[46:49], v172 offset:26176
	s_waitcnt lgkmcnt(1)
	v_mfma_f32_16x16x32_bf16 v[42:45], v[42:45], v[14:17], 0
	s_waitcnt lgkmcnt(0)
	v_mfma_f32_16x16x32_bf16 v[42:45], v[46:49], v[10:13], v[42:45]
	ds_read_b128 v[46:49], v172 offset:26240
	s_waitcnt lgkmcnt(0)
	v_mfma_f32_16x16x32_bf16 v[42:45], v[46:49], v[6:9], v[42:45]
	ds_read_b128 v[46:49], v172 offset:26304
	s_waitcnt lgkmcnt(0)
	v_mfma_f32_16x16x32_bf16 v[42:45], v[46:49], v[2:5], v[42:45]
	s_nop 7
	v_mul_f32_e32 v46, 0x3db504f3, v42
	v_mul_f32_e32 v47, 0x3db504f3, v43
	v_max3_f32 v46, v50, v46, v47
	v_mul_f32_e32 v47, 0x3db504f3, v44
	v_mul_f32_e32 v48, 0x3db504f3, v45
	v_max3_f32 v54, v46, v47, v48
	ds_read_b128 v[46:49], v172 offset:30464
	ds_read_b128 v[50:53], v172 offset:30528
	s_waitcnt lgkmcnt(1)
	v_mfma_f32_16x16x32_bf16 v[46:49], v[46:49], v[14:17], 0
	s_waitcnt lgkmcnt(0)
	v_mfma_f32_16x16x32_bf16 v[46:49], v[50:53], v[10:13], v[46:49]
	ds_read_b128 v[50:53], v172 offset:30592
	s_waitcnt lgkmcnt(0)
	v_mfma_f32_16x16x32_bf16 v[46:49], v[50:53], v[6:9], v[46:49]
	ds_read_b128 v[50:53], v172 offset:30656
	s_waitcnt lgkmcnt(0)
	v_mfma_f32_16x16x32_bf16 v[46:49], v[50:53], v[2:5], v[46:49]
	s_nop 7
	v_mul_f32_e32 v50, 0x3db504f3, v46
	v_mul_f32_e32 v51, 0x3db504f3, v47
	v_max3_f32 v50, v54, v50, v51
	v_mul_f32_e32 v51, 0x3db504f3, v48
	v_mul_f32_e32 v52, 0x3db504f3, v49
	v_max3_f32 v58, v50, v51, v52
	ds_read_b128 v[50:53], v172 offset:34816
	ds_read_b128 v[54:57], v172 offset:34880
	s_waitcnt lgkmcnt(1)
	v_mfma_f32_16x16x32_bf16 v[50:53], v[50:53], v[14:17], 0
	s_waitcnt lgkmcnt(0)
	v_mfma_f32_16x16x32_bf16 v[50:53], v[54:57], v[10:13], v[50:53]
	ds_read_b128 v[54:57], v172 offset:34944
	s_waitcnt lgkmcnt(0)
	v_mfma_f32_16x16x32_bf16 v[50:53], v[54:57], v[6:9], v[50:53]
	ds_read_b128 v[54:57], v172 offset:35008
	s_waitcnt lgkmcnt(0)
	v_mfma_f32_16x16x32_bf16 v[50:53], v[54:57], v[2:5], v[50:53]
	s_nop 7
	v_mul_f32_e32 v54, 0x3db504f3, v50
	v_mul_f32_e32 v55, 0x3db504f3, v51
	v_max3_f32 v54, v58, v54, v55
	v_mul_f32_e32 v55, 0x3db504f3, v52
	v_mul_f32_e32 v56, 0x3db504f3, v53
	v_max3_f32 v62, v54, v55, v56
	ds_read_b128 v[54:57], v172 offset:39168
	ds_read_b128 v[58:61], v172 offset:39232
	s_waitcnt lgkmcnt(1)
	v_mfma_f32_16x16x32_bf16 v[54:57], v[54:57], v[14:17], 0
	s_waitcnt lgkmcnt(0)
	v_mfma_f32_16x16x32_bf16 v[54:57], v[58:61], v[10:13], v[54:57]
	ds_read_b128 v[58:61], v172 offset:39296
	s_waitcnt lgkmcnt(0)
	v_mfma_f32_16x16x32_bf16 v[54:57], v[58:61], v[6:9], v[54:57]
	ds_read_b128 v[58:61], v172 offset:39360
	s_waitcnt lgkmcnt(0)
	v_mfma_f32_16x16x32_bf16 v[54:57], v[58:61], v[2:5], v[54:57]
	s_nop 7
	v_mul_f32_e32 v58, 0x3db504f3, v54
	v_mul_f32_e32 v59, 0x3db504f3, v55
	v_max3_f32 v58, v62, v58, v59
	v_mul_f32_e32 v59, 0x3db504f3, v56
	v_mul_f32_e32 v60, 0x3db504f3, v57
	v_max3_f32 v66, v58, v59, v60
	ds_read_b128 v[58:61], v172 offset:43520
	ds_read_b128 v[62:65], v172 offset:43584
	s_waitcnt lgkmcnt(1)
	v_mfma_f32_16x16x32_bf16 v[58:61], v[58:61], v[14:17], 0
	s_waitcnt lgkmcnt(0)
	v_mfma_f32_16x16x32_bf16 v[58:61], v[62:65], v[10:13], v[58:61]
	ds_read_b128 v[62:65], v172 offset:43648
	s_waitcnt lgkmcnt(0)
	v_mfma_f32_16x16x32_bf16 v[58:61], v[62:65], v[6:9], v[58:61]
	ds_read_b128 v[62:65], v172 offset:43712
	s_waitcnt lgkmcnt(0)
	v_mfma_f32_16x16x32_bf16 v[58:61], v[62:65], v[2:5], v[58:61]
	s_nop 7
	v_mul_f32_e32 v62, 0x3db504f3, v58
	v_mul_f32_e32 v63, 0x3db504f3, v59
	v_max3_f32 v62, v66, v62, v63
	v_mul_f32_e32 v63, 0x3db504f3, v60
	v_mul_f32_e32 v64, 0x3db504f3, v61
	v_max3_f32 v70, v62, v63, v64
	ds_read_b128 v[62:65], v172 offset:47872
	ds_read_b128 v[66:69], v172 offset:47936
	s_waitcnt lgkmcnt(1)
	v_mfma_f32_16x16x32_bf16 v[62:65], v[62:65], v[14:17], 0
	s_waitcnt lgkmcnt(0)
	v_mfma_f32_16x16x32_bf16 v[62:65], v[66:69], v[10:13], v[62:65]
	ds_read_b128 v[66:69], v172 offset:48000
	s_waitcnt lgkmcnt(0)
	v_mfma_f32_16x16x32_bf16 v[62:65], v[66:69], v[6:9], v[62:65]
	ds_read_b128 v[66:69], v172 offset:48064
	s_waitcnt lgkmcnt(0)
	v_mfma_f32_16x16x32_bf16 v[62:65], v[66:69], v[2:5], v[62:65]
	s_nop 7
	v_mul_f32_e32 v66, 0x3db504f3, v62
	v_mul_f32_e32 v67, 0x3db504f3, v63
	v_max3_f32 v66, v70, v66, v67
	v_mul_f32_e32 v67, 0x3db504f3, v64
	v_mul_f32_e32 v68, 0x3db504f3, v65
	v_max3_f32 v74, v66, v67, v68
	ds_read_b128 v[66:69], v172 offset:52224
	ds_read_b128 v[70:73], v172 offset:52288
	s_waitcnt lgkmcnt(1)
	v_mfma_f32_16x16x32_bf16 v[66:69], v[66:69], v[14:17], 0
	s_waitcnt lgkmcnt(0)
	v_mfma_f32_16x16x32_bf16 v[66:69], v[70:73], v[10:13], v[66:69]
	ds_read_b128 v[70:73], v172 offset:52352
	s_waitcnt lgkmcnt(0)
	v_mfma_f32_16x16x32_bf16 v[66:69], v[70:73], v[6:9], v[66:69]
	ds_read_b128 v[70:73], v172 offset:52416
	s_waitcnt lgkmcnt(0)
	v_mfma_f32_16x16x32_bf16 v[66:69], v[70:73], v[2:5], v[66:69]
	s_nop 7
	v_mul_f32_e32 v70, 0x3db504f3, v66
	v_mul_f32_e32 v71, 0x3db504f3, v67
	v_max3_f32 v70, v74, v70, v71
	v_mul_f32_e32 v71, 0x3db504f3, v68
	v_mul_f32_e32 v72, 0x3db504f3, v69
	v_max3_f32 v78, v70, v71, v72
	ds_read_b128 v[70:73], v172 offset:56576
	ds_read_b128 v[74:77], v172 offset:56640
	s_waitcnt lgkmcnt(1)
	v_mfma_f32_16x16x32_bf16 v[70:73], v[70:73], v[14:17], 0
	s_waitcnt lgkmcnt(0)
	v_mfma_f32_16x16x32_bf16 v[70:73], v[74:77], v[10:13], v[70:73]
	ds_read_b128 v[74:77], v172 offset:56704
	s_waitcnt lgkmcnt(0)
	v_mfma_f32_16x16x32_bf16 v[70:73], v[74:77], v[6:9], v[70:73]
	ds_read_b128 v[74:77], v172 offset:56768
	s_waitcnt lgkmcnt(0)
	v_mfma_f32_16x16x32_bf16 v[70:73], v[74:77], v[2:5], v[70:73]
	s_nop 7
	v_mul_f32_e32 v74, 0x3db504f3, v70
	v_mul_f32_e32 v75, 0x3db504f3, v71
	v_max3_f32 v74, v78, v74, v75
	v_mul_f32_e32 v75, 0x3db504f3, v72
	v_mul_f32_e32 v76, 0x3db504f3, v73
	v_max3_f32 v82, v74, v75, v76
	ds_read_b128 v[74:77], v172 offset:60928
	ds_read_b128 v[78:81], v172 offset:60992
	s_waitcnt lgkmcnt(1)
	v_mfma_f32_16x16x32_bf16 v[74:77], v[74:77], v[14:17], 0
	s_waitcnt lgkmcnt(0)
	v_mfma_f32_16x16x32_bf16 v[74:77], v[78:81], v[10:13], v[74:77]
	ds_read_b128 v[78:81], v172 offset:61056
	s_waitcnt lgkmcnt(0)
	v_mfma_f32_16x16x32_bf16 v[74:77], v[78:81], v[6:9], v[74:77]
	ds_read_b128 v[78:81], v172 offset:61120
	s_waitcnt lgkmcnt(0)
	v_mfma_f32_16x16x32_bf16 v[74:77], v[78:81], v[2:5], v[74:77]
	s_nop 7
	v_mul_f32_e32 v78, 0x3db504f3, v74
	v_mul_f32_e32 v79, 0x3db504f3, v75
	v_max3_f32 v78, v82, v78, v79
	v_mul_f32_e32 v79, 0x3db504f3, v76
	v_mul_f32_e32 v80, 0x3db504f3, v77
	v_max3_f32 v82, v78, v79, v80
	ds_read_b128 v[78:81], v172 offset:65280
	s_waitcnt lgkmcnt(0)
	v_mfma_f32_16x16x32_bf16 v[14:17], v[78:81], v[14:17], 0
	ds_read_b128 v[78:81], v172 offset:65344
	s_waitcnt lgkmcnt(0)
	v_mfma_f32_16x16x32_bf16 v[10:13], v[78:81], v[10:13], v[14:17]
	s_nop 4
	ds_read_b128 v[14:17], v172 offset:65408
	s_waitcnt lgkmcnt(0)
	v_mfma_f32_16x16x32_bf16 v[6:9], v[14:17], v[6:9], v[10:13]
	s_nop 2
	ds_read_b128 v[10:13], v172 offset:65472
	s_waitcnt lgkmcnt(0)
	v_mfma_f32_16x16x32_bf16 v[2:5], v[10:13], v[2:5], v[6:9]
	s_nop 7
	v_mul_f32_e32 v6, 0x3db504f3, v2
	v_mul_f32_e32 v7, 0x3db504f3, v3
	v_max3_f32 v6, v82, v6, v7
	v_mul_f32_e32 v7, 0x3db504f3, v4
	v_mul_f32_e32 v8, 0x3db504f3, v5
	v_max3_f32 v6, v6, v7, v8
	v_and_b32_e32 v8, 64, v174
	v_xor_b32_e32 v7, 16, v174
	v_add_u32_e32 v8, 64, v8
	v_cmp_lt_i32_e32 vcc, v7, v8
	s_nop 1
	v_cndmask_b32_e32 v7, v174, v7, vcc
	v_lshlrev_b32_e32 v138, 2, v7
	ds_bpermute_b32 v7, v138, v6
	s_waitcnt lgkmcnt(0)
	v_max_f32_e32 v7, v7, v7
	v_max_f32_e32 v6, v6, v7
	v_xor_b32_e32 v7, 32, v174
	v_cmp_lt_i32_e32 vcc, v7, v8
	s_nop 1
	v_cndmask_b32_e32 v7, v174, v7, vcc
	v_lshlrev_b32_e32 v139, 2, v7
	ds_bpermute_b32 v7, v139, v6
	s_waitcnt lgkmcnt(0)
	v_max_f32_e32 v7, v7, v7
	v_max_f32_e32 v175, v6, v7
	v_fma_f32 v7, v19, s25, -v175
	v_mul_f32_e32 v7, 0x3fb8aa3b, v7
	v_exp_f32_e32 v95, v7
	v_fma_f32 v7, v20, s25, -v175
	v_mul_f32_e32 v7, 0x3fb8aa3b, v7
	v_exp_f32_e32 v96, v7
	v_fma_f32 v7, v21, s25, -v175
	v_mul_f32_e32 v7, 0x3fb8aa3b, v7
	v_exp_f32_e32 v97, v7
	v_fma_f32 v7, v22, s25, -v175
	v_mul_f32_e32 v7, 0x3fb8aa3b, v7
	v_exp_f32_e32 v133, v7
	v_fma_f32 v7, v23, s25, -v175
	v_mul_f32_e32 v7, 0x3fb8aa3b, v7
	v_exp_f32_e32 v135, v7
	v_fma_f32 v7, v24, s25, -v175
	v_mul_f32_e32 v7, 0x3fb8aa3b, v7
	v_exp_f32_e32 v136, v7
	v_fma_f32 v7, v25, s25, -v175
	v_mul_f32_e32 v7, 0x3fb8aa3b, v7
	v_exp_f32_e32 v137, v7
	v_fma_f32 v7, v26, s25, -v175
	v_mul_f32_e32 v7, 0x3fb8aa3b, v7
	v_exp_f32_e32 v86, v7
	v_fma_f32 v7, v27, s25, -v175
	v_mul_f32_e32 v7, 0x3fb8aa3b, v7
	v_exp_f32_e32 v87, v7
	v_fma_f32 v7, v28, s25, -v175
	v_mul_f32_e32 v7, 0x3fb8aa3b, v7
	v_exp_f32_e32 v88, v7
	v_fma_f32 v7, v29, s25, -v175
	v_mul_f32_e32 v7, 0x3fb8aa3b, v7
	v_exp_f32_e32 v89, v7
	v_fma_f32 v7, v30, s25, -v175
	v_mul_f32_e32 v7, 0x3fb8aa3b, v7
	v_exp_f32_e32 v90, v7
	v_fma_f32 v7, v31, s25, -v175
	v_mul_f32_e32 v7, 0x3fb8aa3b, v7
	v_exp_f32_e32 v91, v7
	v_fma_f32 v7, v32, s25, -v175
	v_mul_f32_e32 v7, 0x3fb8aa3b, v7
	v_exp_f32_e32 v92, v7
	v_fma_f32 v7, v33, s25, -v175
	v_mul_f32_e32 v7, 0x3fb8aa3b, v7
	v_exp_f32_e32 v93, v7
	v_fma_f32 v7, v34, s25, -v175
	v_mul_f32_e32 v7, 0x3fb8aa3b, v7
	v_exp_f32_e32 v78, v7
	v_fma_f32 v7, v35, s25, -v175
	v_mul_f32_e32 v7, 0x3fb8aa3b, v7
	v_exp_f32_e32 v79, v7
	v_fma_f32 v7, v36, s25, -v175
	v_mul_f32_e32 v7, 0x3fb8aa3b, v7
	v_exp_f32_e32 v80, v7
	v_fma_f32 v7, v37, s25, -v175
	v_mul_f32_e32 v7, 0x3fb8aa3b, v7
	v_exp_f32_e32 v81, v7
	v_fma_f32 v7, v38, s25, -v175
	v_mul_f32_e32 v7, 0x3fb8aa3b, v7
	v_exp_f32_e32 v82, v7
	v_fma_f32 v7, v39, s25, -v175
	v_mul_f32_e32 v7, 0x3fb8aa3b, v7
	v_exp_f32_e32 v83, v7
	v_fma_f32 v7, v40, s25, -v175
	v_mul_f32_e32 v7, 0x3fb8aa3b, v7
	v_exp_f32_e32 v84, v7
	v_fma_f32 v7, v41, s25, -v175
	v_mul_f32_e32 v7, 0x3fb8aa3b, v7
	v_exp_f32_e32 v85, v7
	v_fma_f32 v7, v42, s25, -v175
	v_mul_f32_e32 v7, 0x3fb8aa3b, v7
	v_exp_f32_e32 v36, v7
	v_fma_f32 v7, v43, s25, -v175
	v_mul_f32_e32 v7, 0x3fb8aa3b, v7
	v_exp_f32_e32 v37, v7
	v_fma_f32 v7, v44, s25, -v175
	v_mul_f32_e32 v7, 0x3fb8aa3b, v7
	v_exp_f32_e32 v38, v7
	v_fma_f32 v7, v45, s25, -v175
	v_fma_f32 v6, v18, s25, -v175
	v_mul_f32_e32 v7, 0x3fb8aa3b, v7
	v_mul_f32_e32 v6, 0x3fb8aa3b, v6
	v_exp_f32_e32 v39, v7
	v_fma_f32 v7, v46, s25, -v175
	v_exp_f32_e32 v94, v6
	v_mul_f32_e32 v7, 0x3fb8aa3b, v7
	v_exp_f32_e32 v40, v7
	v_fma_f32 v7, v47, s25, -v175
	v_mul_f32_e32 v7, 0x3fb8aa3b, v7
	v_exp_f32_e32 v41, v7
	v_fma_f32 v7, v48, s25, -v175
	v_add_f32_e32 v6, 0, v94
	v_mul_f32_e32 v7, 0x3fb8aa3b, v7
	v_add_f32_e32 v6, v95, v6
	v_exp_f32_e32 v42, v7
	v_fma_f32 v7, v49, s25, -v175
	v_add_f32_e32 v6, v96, v6
	v_mul_f32_e32 v7, 0x3fb8aa3b, v7
	v_add_f32_e32 v6, v97, v6
	v_exp_f32_e32 v43, v7
	v_fma_f32 v7, v50, s25, -v175
	v_add_f32_e32 v6, v133, v6
	v_mul_f32_e32 v7, 0x3fb8aa3b, v7
	v_add_f32_e32 v6, v135, v6
	v_exp_f32_e32 v28, v7
	v_fma_f32 v7, v51, s25, -v175
	v_add_f32_e32 v6, v136, v6
	v_mul_f32_e32 v7, 0x3fb8aa3b, v7
	v_add_f32_e32 v6, v137, v6
	v_exp_f32_e32 v29, v7
	v_fma_f32 v7, v52, s25, -v175
	v_add_f32_e32 v6, v86, v6
	v_mul_f32_e32 v7, 0x3fb8aa3b, v7
	v_add_f32_e32 v6, v87, v6
	v_exp_f32_e32 v30, v7
	v_fma_f32 v7, v53, s25, -v175
	v_add_f32_e32 v6, v88, v6
	v_mul_f32_e32 v7, 0x3fb8aa3b, v7
	v_add_f32_e32 v6, v89, v6
	v_exp_f32_e32 v31, v7
	v_fma_f32 v7, v54, s25, -v175
	v_add_f32_e32 v6, v90, v6
	v_mul_f32_e32 v7, 0x3fb8aa3b, v7
	v_add_f32_e32 v6, v91, v6
	v_exp_f32_e32 v32, v7
	v_fma_f32 v7, v55, s25, -v175
	v_add_f32_e32 v6, v92, v6
	v_mul_f32_e32 v7, 0x3fb8aa3b, v7
	v_add_f32_e32 v6, v93, v6
	v_exp_f32_e32 v33, v7
	v_fma_f32 v7, v56, s25, -v175
	v_add_f32_e32 v6, v78, v6
	v_mul_f32_e32 v7, 0x3fb8aa3b, v7
	v_add_f32_e32 v6, v79, v6
	v_exp_f32_e32 v34, v7
	v_fma_f32 v7, v57, s25, -v175
	v_add_f32_e32 v6, v80, v6
	v_mul_f32_e32 v7, 0x3fb8aa3b, v7
	v_add_f32_e32 v6, v81, v6
	v_exp_f32_e32 v35, v7
	v_fma_f32 v7, v58, s25, -v175
	v_add_f32_e32 v6, v82, v6
	v_mul_f32_e32 v7, 0x3fb8aa3b, v7
	v_add_f32_e32 v6, v83, v6
	v_exp_f32_e32 v20, v7
	v_fma_f32 v7, v59, s25, -v175
	v_add_f32_e32 v6, v84, v6
	v_mul_f32_e32 v7, 0x3fb8aa3b, v7
	v_add_f32_e32 v6, v85, v6
	v_exp_f32_e32 v21, v7
	v_fma_f32 v7, v60, s25, -v175
	v_add_f32_e32 v6, v36, v6
	v_mul_f32_e32 v7, 0x3fb8aa3b, v7
	v_add_f32_e32 v6, v37, v6
	v_exp_f32_e32 v22, v7
	v_fma_f32 v7, v61, s25, -v175
	v_add_f32_e32 v6, v38, v6
	v_mul_f32_e32 v7, 0x3fb8aa3b, v7
	v_add_f32_e32 v6, v39, v6
	v_exp_f32_e32 v23, v7
	v_fma_f32 v7, v62, s25, -v175
	v_add_f32_e32 v6, v40, v6
	v_mul_f32_e32 v7, 0x3fb8aa3b, v7
	v_add_f32_e32 v6, v41, v6
	v_exp_f32_e32 v24, v7
	v_fma_f32 v7, v63, s25, -v175
	v_add_f32_e32 v6, v42, v6
	v_mul_f32_e32 v7, 0x3fb8aa3b, v7
	v_add_f32_e32 v6, v43, v6
	v_exp_f32_e32 v25, v7
	v_fma_f32 v7, v64, s25, -v175
	v_add_f32_e32 v6, v28, v6
	v_mul_f32_e32 v7, 0x3fb8aa3b, v7
	v_add_f32_e32 v6, v29, v6
	v_exp_f32_e32 v26, v7
	v_fma_f32 v7, v65, s25, -v175
	v_add_f32_e32 v6, v30, v6
	v_mul_f32_e32 v7, 0x3fb8aa3b, v7
	v_add_f32_e32 v6, v31, v6
	v_exp_f32_e32 v27, v7
	v_fma_f32 v7, v66, s25, -v175
	v_add_f32_e32 v6, v32, v6
	v_mul_f32_e32 v7, 0x3fb8aa3b, v7
	v_add_f32_e32 v6, v33, v6
	v_exp_f32_e32 v12, v7
	v_fma_f32 v7, v67, s25, -v175
	v_add_f32_e32 v6, v34, v6
	v_mul_f32_e32 v7, 0x3fb8aa3b, v7
	v_add_f32_e32 v6, v35, v6
	v_exp_f32_e32 v13, v7
	v_fma_f32 v7, v68, s25, -v175
	v_add_f32_e32 v6, v20, v6
	v_mul_f32_e32 v7, 0x3fb8aa3b, v7
	v_add_f32_e32 v6, v21, v6
	v_exp_f32_e32 v14, v7
	v_fma_f32 v7, v69, s25, -v175
	v_add_f32_e32 v6, v22, v6
	v_mul_f32_e32 v7, 0x3fb8aa3b, v7
	v_add_f32_e32 v6, v23, v6
	v_exp_f32_e32 v15, v7
	v_fma_f32 v7, v70, s25, -v175
	v_add_f32_e32 v6, v24, v6
	v_mul_f32_e32 v7, 0x3fb8aa3b, v7
	v_add_f32_e32 v6, v25, v6
	v_exp_f32_e32 v16, v7
	v_fma_f32 v7, v71, s25, -v175
	v_add_f32_e32 v6, v26, v6
	v_mul_f32_e32 v7, 0x3fb8aa3b, v7
	v_add_f32_e32 v6, v27, v6
	v_exp_f32_e32 v17, v7
	v_fma_f32 v7, v72, s25, -v175
	v_add_f32_e32 v6, v12, v6
	v_mul_f32_e32 v7, 0x3fb8aa3b, v7
	v_add_f32_e32 v6, v13, v6
	v_exp_f32_e32 v18, v7
	v_fma_f32 v7, v73, s25, -v175
	v_add_f32_e32 v6, v14, v6
	v_mul_f32_e32 v7, 0x3fb8aa3b, v7
	v_add_f32_e32 v6, v15, v6
	v_exp_f32_e32 v19, v7
	v_add_f32_e32 v6, v16, v6
	v_add_f32_e32 v6, v17, v6
	v_add_f32_e32 v6, v18, v6
	v_add_f32_e32 v7, v19, v6
	v_fma_f32 v6, v74, s25, -v175
	v_mul_f32_e32 v6, 0x3fb8aa3b, v6
	v_exp_f32_e32 v6, v6
	v_cvt_pk_bf16_f32 v44, v94, v95
	v_cvt_pk_bf16_f32 v45, v96, v97
	v_cvt_pk_bf16_f32 v46, v133, v135
	v_cvt_pk_bf16_f32 v47, v136, v137
	ds_read2_b64 v[48:51], v144 offset1:4
	v_add_f32_e32 v8, v6, v7
	v_fma_f32 v7, v75, s25, -v175
	ds_read2_b64 v[52:55], v145 offset0:2 offset1:6
	ds_read2_b64 v[56:59], v146 offset0:4 offset1:8
	ds_read2_b64 v[60:63], v147 offset0:6 offset1:10
	ds_read2_b64 v[64:67], v148 offset0:8 offset1:12
	ds_read2_b64 v[68:71], v149 offset0:10 offset1:14
	ds_read2_b64 v[72:75], v150 offset0:12 offset1:16
	ds_read2_b64 v[94:97], v151 offset0:14 offset1:18
	v_cvt_pk_bf16_f32 v86, v86, v87
	v_cvt_pk_bf16_f32 v87, v88, v89
	v_cvt_pk_bf16_f32 v88, v90, v91
	v_cvt_pk_bf16_f32 v89, v92, v93
	ds_read2_b64 v[90:93], v144 offset0:8 offset1:12
	s_waitcnt lgkmcnt(8)
	v_mfma_f32_16x16x32_bf16 v[48:51], v[48:51], v[44:47], 0
	v_mul_f32_e32 v7, 0x3fb8aa3b, v7
	v_exp_f32_e32 v7, v7
	v_fma_f32 v2, v2, s25, -v175
	s_waitcnt lgkmcnt(0)
	v_mfma_f32_16x16x32_bf16 v[48:51], v[90:93], v[86:89], v[48:51]
	ds_read2_b64 v[90:93], v145 offset0:10 offset1:14
	v_add_f32_e32 v9, v7, v8
	v_fma_f32 v8, v76, s25, -v175
	v_mfma_f32_16x16x32_bf16 v[52:55], v[52:55], v[44:47], 0
	v_mul_f32_e32 v8, 0x3fb8aa3b, v8
	v_exp_f32_e32 v8, v8
	v_mul_f32_e32 v2, 0x3fb8aa3b, v2
	s_waitcnt lgkmcnt(0)
	v_mfma_f32_16x16x32_bf16 v[52:55], v[90:93], v[86:89], v[52:55]
	ds_read2_b64 v[90:93], v146 offset0:12 offset1:16
	v_add_f32_e32 v10, v8, v9
	v_fma_f32 v9, v77, s25, -v175
	v_mfma_f32_16x16x32_bf16 v[56:59], v[56:59], v[44:47], 0
	v_mul_f32_e32 v9, 0x3fb8aa3b, v9
	v_exp_f32_e32 v9, v9
	v_fma_f32 v3, v3, s25, -v175
	s_waitcnt lgkmcnt(0)
	v_mfma_f32_16x16x32_bf16 v[56:59], v[90:93], v[86:89], v[56:59]
	ds_read2_b64 v[90:93], v147 offset0:14 offset1:18
	v_add_f32_e32 v11, v9, v10
	v_exp_f32_e32 v10, v2
	v_mfma_f32_16x16x32_bf16 v[60:63], v[60:63], v[44:47], 0
	v_mul_f32_e32 v3, 0x3fb8aa3b, v3
	v_mov_b32_e32 v133, v99
	v_add_f32_e32 v2, v10, v11
	s_waitcnt lgkmcnt(0)
	v_mfma_f32_16x16x32_bf16 v[60:63], v[90:93], v[86:89], v[60:63]
	ds_read2_b64 v[90:93], v148 offset0:16 offset1:20
	v_exp_f32_e32 v11, v3
	v_fma_f32 v3, v4, s25, -v175
	v_mfma_f32_16x16x32_bf16 v[64:67], v[64:67], v[44:47], 0
	v_mul_f32_e32 v3, 0x3fb8aa3b, v3
	v_exp_f32_e32 v4, v3
	v_fma_f32 v3, v5, s25, -v175
	s_waitcnt lgkmcnt(0)
	v_mfma_f32_16x16x32_bf16 v[64:67], v[90:93], v[86:89], v[64:67]
	ds_read2_b64 v[90:93], v149 offset0:18 offset1:22
	v_mul_f32_e32 v3, 0x3fb8aa3b, v3
	v_exp_f32_e32 v5, v3
	v_mfma_f32_16x16x32_bf16 v[68:71], v[68:71], v[44:47], 0
	v_add_f32_e32 v2, v11, v2
	v_add_f32_e32 v2, v4, v2
	v_add_f32_e32 v2, v5, v2
	s_waitcnt lgkmcnt(0)
	v_mfma_f32_16x16x32_bf16 v[68:71], v[90:93], v[86:89], v[68:71]
	ds_read2_b64 v[90:93], v150 offset0:20 offset1:24
	ds_bpermute_b32 v3, v138, v2
	v_mov_b32_e32 v135, v99
	v_mfma_f32_16x16x32_bf16 v[72:75], v[72:75], v[44:47], 0
	s_waitcnt lgkmcnt(0)
	v_add_f32_e32 v2, v2, v3
	v_mfma_f32_16x16x32_bf16 v[72:75], v[90:93], v[86:89], v[72:75]
	ds_read2_b64 v[90:93], v151 offset0:22 offset1:26
	v_cvt_pk_bf16_f32 v76, v78, v79
	v_cvt_pk_bf16_f32 v77, v80, v81
	v_cvt_pk_bf16_f32 v78, v82, v83
	v_cvt_pk_bf16_f32 v79, v84, v85
	ds_read2_b64 v[80:83], v144 offset0:16 offset1:20
	s_waitcnt lgkmcnt(0)
	v_mfma_f32_16x16x32_bf16 v[48:51], v[80:83], v[76:79], v[48:51]
	ds_read2_b64 v[80:83], v145 offset0:18 offset1:22
	ds_bpermute_b32 v3, v139, v2
	s_waitcnt lgkmcnt(0)
	v_add_f32_e32 v2, v2, v3
	v_mfma_f32_16x16x32_bf16 v[52:55], v[80:83], v[76:79], v[52:55]
	ds_read2_b64 v[80:83], v146 offset0:20 offset1:24
	v_div_scale_f32 v3, s[12:13], v2, v2, 1.0
	s_waitcnt lgkmcnt(0)
	v_mfma_f32_16x16x32_bf16 v[56:59], v[80:83], v[76:79], v[56:59]
	ds_read2_b64 v[80:83], v147 offset0:22 offset1:26
	s_waitcnt lgkmcnt(0)
	v_mfma_f32_16x16x32_bf16 v[60:63], v[80:83], v[76:79], v[60:63]
	ds_read2_b64 v[80:83], v148 offset0:24 offset1:28
	s_waitcnt lgkmcnt(0)
	v_mfma_f32_16x16x32_bf16 v[64:67], v[80:83], v[76:79], v[64:67]
	ds_read2_b64 v[80:83], v149 offset0:26 offset1:30
	s_waitcnt lgkmcnt(0)
	v_mfma_f32_16x16x32_bf16 v[68:71], v[80:83], v[76:79], v[68:71]
	ds_read2_b64 v[80:83], v150 offset0:28 offset1:32
	s_waitcnt lgkmcnt(0)
	v_mfma_f32_16x16x32_bf16 v[72:75], v[80:83], v[76:79], v[72:75]
	ds_read2_b64 v[80:83], v151 offset0:30 offset1:34
	v_cvt_pk_bf16_f32 v36, v36, v37
	v_cvt_pk_bf16_f32 v37, v38, v39
	v_cvt_pk_bf16_f32 v38, v40, v41
	v_cvt_pk_bf16_f32 v39, v42, v43
	ds_read2_b64 v[40:43], v144 offset0:24 offset1:28
	s_waitcnt lgkmcnt(0)
	v_mfma_f32_16x16x32_bf16 v[40:43], v[40:43], v[36:39], v[48:51]
	s_nop 2
	ds_read2_b64 v[48:51], v145 offset0:26 offset1:30
	s_waitcnt lgkmcnt(0)
	v_mfma_f32_16x16x32_bf16 v[48:51], v[48:51], v[36:39], v[52:55]
	s_nop 2
	ds_read2_b64 v[52:55], v146 offset0:28 offset1:32
	s_waitcnt lgkmcnt(0)
	v_mfma_f32_16x16x32_bf16 v[52:55], v[52:55], v[36:39], v[56:59]
	s_nop 2
	ds_read2_b64 v[56:59], v147 offset0:30 offset1:34
	s_waitcnt lgkmcnt(0)
	v_mfma_f32_16x16x32_bf16 v[56:59], v[56:59], v[36:39], v[60:63]
	s_nop 2
	ds_read2_b64 v[60:63], v148 offset0:32 offset1:36
	s_waitcnt lgkmcnt(0)
	v_mfma_f32_16x16x32_bf16 v[60:63], v[60:63], v[36:39], v[64:67]
	s_nop 2
	ds_read2_b64 v[64:67], v149 offset0:34 offset1:38
	s_waitcnt lgkmcnt(0)
	v_mfma_f32_16x16x32_bf16 v[64:67], v[64:67], v[36:39], v[68:71]
	s_nop 2
	ds_read2_b64 v[68:71], v150 offset0:36 offset1:40
	s_waitcnt lgkmcnt(0)
	v_mfma_f32_16x16x32_bf16 v[68:71], v[68:71], v[36:39], v[72:75]
	s_nop 2
	ds_read2_b64 v[72:75], v151 offset0:38 offset1:42
	v_cvt_pk_bf16_f32 v28, v28, v29
	v_cvt_pk_bf16_f32 v29, v30, v31
	v_cvt_pk_bf16_f32 v30, v32, v33
	v_cvt_pk_bf16_f32 v31, v34, v35
	ds_read2_b64 v[32:35], v144 offset0:32 offset1:36
	v_mfma_f32_16x16x32_bf16 v[44:47], v[94:97], v[44:47], 0
	s_waitcnt lgkmcnt(0)
	v_mfma_f32_16x16x32_bf16 v[32:35], v[32:35], v[28:31], v[40:43]
	s_nop 2
	ds_read2_b64 v[40:43], v145 offset0:34 offset1:38
	v_mfma_f32_16x16x32_bf16 v[44:47], v[90:93], v[86:89], v[44:47]
	v_mfma_f32_16x16x32_bf16 v[44:47], v[80:83], v[76:79], v[44:47]
	v_mfma_f32_16x16x32_bf16 v[36:39], v[72:75], v[36:39], v[44:47]
	s_waitcnt lgkmcnt(0)
	v_mfma_f32_16x16x32_bf16 v[40:43], v[40:43], v[28:31], v[48:51]
	s_nop 4
	ds_read2_b64 v[44:47], v146 offset0:36 offset1:40
	ds_read2_b64 v[48:51], v147 offset0:38 offset1:42
	s_waitcnt lgkmcnt(1)
	v_mfma_f32_16x16x32_bf16 v[44:47], v[44:47], v[28:31], v[52:55]
	s_nop 2
	ds_read2_b64 v[52:55], v148 offset0:40 offset1:44
	s_waitcnt lgkmcnt(1)
	v_mfma_f32_16x16x32_bf16 v[48:51], v[48:51], v[28:31], v[56:59]
	s_nop 2
	ds_read2_b64 v[56:59], v149 offset0:42 offset1:46
	s_waitcnt lgkmcnt(1)
	v_mfma_f32_16x16x32_bf16 v[52:55], v[52:55], v[28:31], v[60:63]
	s_nop 2
	ds_read2_b64 v[60:63], v150 offset0:44 offset1:48
	s_waitcnt lgkmcnt(1)
	v_mfma_f32_16x16x32_bf16 v[56:59], v[56:59], v[28:31], v[64:67]
	s_nop 2
	ds_read2_b64 v[64:67], v151 offset0:46 offset1:50
	v_cvt_pk_bf16_f32 v20, v20, v21
	v_cvt_pk_bf16_f32 v21, v22, v23
	v_cvt_pk_bf16_f32 v22, v24, v25
	v_cvt_pk_bf16_f32 v23, v26, v27
	ds_read2_b64 v[24:27], v144 offset0:40 offset1:44
	s_waitcnt lgkmcnt(0)
	v_mfma_f32_16x16x32_bf16 v[24:27], v[24:27], v[20:23], v[32:35]
	s_nop 2
	ds_read2_b64 v[32:35], v145 offset0:42 offset1:46
	v_mfma_f32_16x16x32_bf16 v[60:63], v[60:63], v[28:31], v[68:71]
	v_mfma_f32_16x16x32_bf16 v[28:31], v[64:67], v[28:31], v[36:39]
	s_waitcnt lgkmcnt(0)
	v_mfma_f32_16x16x32_bf16 v[32:35], v[32:35], v[20:23], v[40:43]
	s_nop 0
	ds_read2_b64 v[36:39], v146 offset0:44 offset1:48
	s_nop 0
	ds_read2_b64 v[40:43], v147 offset0:46 offset1:50
	s_waitcnt lgkmcnt(1)
	v_mfma_f32_16x16x32_bf16 v[36:39], v[36:39], v[20:23], v[44:47]
	s_nop 2
	ds_read2_b64 v[44:47], v148 offset0:48 offset1:52
	s_waitcnt lgkmcnt(1)
	v_mfma_f32_16x16x32_bf16 v[40:43], v[40:43], v[20:23], v[48:51]
	s_nop 2
	ds_read2_b64 v[48:51], v149 offset0:50 offset1:54
	s_waitcnt lgkmcnt(1)
	v_mfma_f32_16x16x32_bf16 v[44:47], v[44:47], v[20:23], v[52:55]
	s_nop 2
	ds_read2_b64 v[52:55], v150 offset0:52 offset1:56
	s_waitcnt lgkmcnt(1)
	v_mfma_f32_16x16x32_bf16 v[48:51], v[48:51], v[20:23], v[56:59]
	s_nop 2
	ds_read_b64 v[56:57], v151 offset:432
	ds_read_b64 v[58:59], v152
	v_cvt_pk_bf16_f32 v12, v12, v13
	v_cvt_pk_bf16_f32 v13, v14, v15
	v_cvt_pk_bf16_f32 v14, v16, v17
	v_cvt_pk_bf16_f32 v15, v18, v19
	ds_read2_b64 v[16:19], v144 offset0:48 offset1:52
	s_waitcnt lgkmcnt(0)
	v_mfma_f32_16x16x32_bf16 v[16:19], v[16:19], v[12:15], v[24:27]
	s_nop 2
	ds_read2_b64 v[24:27], v145 offset0:50 offset1:54
	v_mfma_f32_16x16x32_bf16 v[52:55], v[52:55], v[20:23], v[60:63]
	v_mfma_f32_16x16x32_bf16 v[20:23], v[56:59], v[20:23], v[28:31]
	s_nop 2
	ds_read2_b64 v[28:31], v146 offset0:52 offset1:56
	s_waitcnt lgkmcnt(1)
	v_mfma_f32_16x16x32_bf16 v[24:27], v[24:27], v[12:15], v[32:35]
	s_nop 2
	ds_read_b64 v[32:33], v147 offset:432
	ds_read_b64 v[34:35], v153
	s_waitcnt lgkmcnt(2)
	v_mfma_f32_16x16x32_bf16 v[28:31], v[28:31], v[12:15], v[36:39]
	s_nop 2
	ds_read_b64 v[36:37], v148 offset:448
	ds_read_b64 v[38:39], v154
	s_waitcnt lgkmcnt(2)
	v_mfma_f32_16x16x32_bf16 v[32:35], v[32:35], v[12:15], v[40:43]
	s_nop 2
	ds_read_b64 v[40:41], v155
	ds_read_b64 v[42:43], v156
	s_waitcnt lgkmcnt(2)
	v_mfma_f32_16x16x32_bf16 v[36:39], v[36:39], v[12:15], v[44:47]
	s_nop 2
	ds_read_b64 v[44:45], v157
	ds_read_b64 v[46:47], v150
	s_waitcnt lgkmcnt(2)
	v_mfma_f32_16x16x32_bf16 v[40:43], v[40:43], v[12:15], v[48:51]
	s_nop 2
	ds_read_b64 v[48:49], v158
	ds_read_b64 v[50:51], v151 offset:16
	v_cvt_pk_bf16_f32 v6, v6, v7
	v_cvt_pk_bf16_f32 v7, v8, v9
	s_waitcnt lgkmcnt(2)
	v_mfma_f32_16x16x32_bf16 v[44:47], v[44:47], v[12:15], v[52:55]
	v_cvt_pk_bf16_f32 v8, v10, v11
	v_cvt_pk_bf16_f32 v9, v4, v5
	s_waitcnt lgkmcnt(0)
	v_mfma_f32_16x16x32_bf16 v[12:15], v[48:51], v[12:15], v[20:23]
	s_nop 2
	ds_read_b64 v[20:21], v144 offset:448
	ds_read_b64 v[22:23], v159
	s_waitcnt lgkmcnt(0)
	v_mfma_f32_16x16x32_bf16 v[16:19], v[20:23], v[6:9], v[16:19]
	ds_read_b64 v[20:21], v145 offset:464
	ds_read_b64 v[22:23], v160
	s_waitcnt lgkmcnt(0)
	v_mfma_f32_16x16x32_bf16 v[20:23], v[20:23], v[6:9], v[24:27]
	s_nop 2
	ds_read_b64 v[24:25], v161
	ds_read_b64 v[26:27], v146
	s_waitcnt lgkmcnt(0)
	v_mfma_f32_16x16x32_bf16 v[24:27], v[24:27], v[6:9], v[28:31]
	s_nop 2
	ds_read_b64 v[28:29], v162
	ds_read_b64 v[30:31], v147 offset:16
	s_waitcnt lgkmcnt(0)
	v_mfma_f32_16x16x32_bf16 v[28:31], v[28:31], v[6:9], v[32:35]
	s_nop 2
	ds_read2_b64 v[32:35], v148 offset1:4
	s_waitcnt lgkmcnt(0)
	v_mfma_f32_16x16x32_bf16 v[32:35], v[32:35], v[6:9], v[36:39]
	s_nop 2
	ds_read2_b64 v[36:39], v149 offset0:2 offset1:6
	s_waitcnt lgkmcnt(0)
	v_mfma_f32_16x16x32_bf16 v[36:39], v[36:39], v[6:9], v[40:43]
	s_nop 2
	ds_read2_b64 v[40:43], v150 offset0:4 offset1:8
	s_waitcnt lgkmcnt(0)
	v_mfma_f32_16x16x32_bf16 v[40:43], v[40:43], v[6:9], v[44:47]
	s_nop 2
	ds_read2_b64 v[44:47], v151 offset0:6 offset1:10
	s_waitcnt lgkmcnt(0)
	v_mfma_f32_16x16x32_bf16 v[4:7], v[44:47], v[6:9], v[12:15]
	v_rcp_f32_e32 v8, v3
	s_nop 0
	v_fma_f32 v9, -v3, v8, 1.0
	v_fmac_f32_e32 v8, v9, v8
	v_div_scale_f32 v9, vcc, 1.0, v2, 1.0
	v_mul_f32_e32 v10, v9, v8
	v_fma_f32 v11, -v3, v10, v9
	v_fmac_f32_e32 v10, v11, v8
	v_fma_f32 v3, -v3, v10, v9
	v_div_fmas_f32 v3, v3, v8, v10
	v_div_fixup_f32 v10, v3, v2, 1.0
	v_mul_f32_e32 v8, v10, v16
	v_mul_f32_e32 v9, v10, v17
	v_lshl_add_u64 v[2:3], s[0:1], 0, v[132:133]
	v_cvt_pk_bf16_f32 v8, v8, v9
	v_mul_f32_e32 v9, v10, v18
	v_lshl_add_u64 v[2:3], v[2:3], 0, v[134:135]
	v_mul_f32_e32 v11, v10, v19
	v_cvt_pk_bf16_f32 v9, v9, v11
	global_store_dwordx2 v[2:3], v[8:9], off
	v_mul_f32_e32 v8, v10, v20
	v_mul_f32_e32 v9, v10, v21
	v_cvt_pk_bf16_f32 v8, v8, v9
	v_mul_f32_e32 v9, v10, v22
	v_mul_f32_e32 v11, v10, v23
	v_cvt_pk_bf16_f32 v9, v9, v11
	global_store_dwordx2 v[2:3], v[8:9], off offset:32
	v_mul_f32_e32 v8, v10, v24
	v_mul_f32_e32 v9, v10, v25
	v_cvt_pk_bf16_f32 v8, v8, v9
	v_mul_f32_e32 v9, v10, v26
	v_mul_f32_e32 v11, v10, v27
	v_cvt_pk_bf16_f32 v9, v9, v11
	global_store_dwordx2 v[2:3], v[8:9], off offset:64
	v_mul_f32_e32 v8, v10, v28
	v_mul_f32_e32 v9, v10, v29
	v_cvt_pk_bf16_f32 v8, v8, v9
	v_mul_f32_e32 v9, v10, v30
	v_mul_f32_e32 v11, v10, v31
	v_cvt_pk_bf16_f32 v9, v9, v11
	global_store_dwordx2 v[2:3], v[8:9], off offset:96
	v_mul_f32_e32 v8, v10, v32
	v_mul_f32_e32 v9, v10, v33
	v_cvt_pk_bf16_f32 v8, v8, v9
	v_mul_f32_e32 v9, v10, v34
	v_mul_f32_e32 v11, v10, v35
	v_cvt_pk_bf16_f32 v9, v9, v11
	global_store_dwordx2 v[2:3], v[8:9], off offset:128
	v_mul_f32_e32 v8, v10, v36
	v_mul_f32_e32 v9, v10, v37
	v_cvt_pk_bf16_f32 v8, v8, v9
	v_mul_f32_e32 v9, v10, v38
	v_mul_f32_e32 v11, v10, v39
	v_cvt_pk_bf16_f32 v9, v9, v11
	global_store_dwordx2 v[2:3], v[8:9], off offset:160
	v_mul_f32_e32 v8, v10, v40
	v_mul_f32_e32 v9, v10, v41
	v_cvt_pk_bf16_f32 v8, v8, v9
	v_mul_f32_e32 v9, v10, v42
	v_mul_f32_e32 v4, v10, v4
	v_mul_f32_e32 v5, v10, v5
	v_mul_f32_e32 v11, v10, v43
	v_cvt_pk_bf16_f32 v9, v9, v11
	global_store_dwordx2 v[2:3], v[8:9], off offset:192
	v_cvt_pk_bf16_f32 v4, v4, v5
	v_mul_f32_e32 v5, v10, v6
	v_mul_f32_e32 v6, v10, v7
	v_cvt_pk_bf16_f32 v5, v5, v6
	global_store_dwordx2 v[2:3], v[4:5], off offset:224
	s_cbranch_scc1 .LBB0_1113
